# GEMM K-loops: LDS-DMA loads use SGPR-base + 32-bit lane offset addressing, removing the 64-bit VALU address adds from the load phases
# speedup vs baseline: 1.0061x; 1.0061x over previous
; #define PG8_STAGE(bufoff, gbase, voff) do { _Pragma("unroll") for (int _i = 0; _i < 2; ++_i) \
;         __builtin_amdgcn_global_load_lds((const unsigned*)((const char*)(gbase) + (voff)[_i]), (PG8_LAS unsigned*)(lds + (bufoff) + ldsw + _i * 8192), 16, 0, 0); } while (0)
; #define PG8_LDA(dst, b, h) do { _Pragma("unroll") for (int m = 0; m < 4; ++m) _Pragma("unroll") for (int k = 0; k < 2; ++k) dst[m][k] = *(const PG8_LAS bf16x8*)(lds + PG8_SA(b, h) + aoff + m * 2048 + k * 1024); } while (0)
; #define PG8_LDB(dst, b, h) do { _Pragma("unroll") for (int n = 0; n < 2; ++n) _Pragma("unroll") for (int k = 0; k < 2; ++k) dst[n][k] = *(const PG8_LAS bf16x8*)(lds + PG8_SB(b, h) + boff + n * 2048 + k * 1024); } while (0)
; #define PG8_MMA(ai, bj, At, Bt) do { __builtin_amdgcn_s_setprio(1); _Pragma("unroll") for (int m = 0; m < 4; ++m) _Pragma("unroll") for (int n = 0; n < 2; ++n) _Pragma("unroll") for (int k = 0; k < 2; ++k) \
;         acc[ai][bj][m][n] = __builtin_amdgcn_mfma_f32_16x16x32_bf16(Bt[n][k], At[m][k], acc[ai][bj][m][n], 0, 0, 0); __builtin_amdgcn_s_setprio(0); } while (0)
; #define PG8_WAIT_V(n) asm volatile("s_waitcnt vmcnt(" #n ")" ::: "memory")
; #define PG8_WAIT_L(n) asm volatile("s_waitcnt lgkmcnt(" #n ")" ::: "memory")
; #define PG8_BAR __builtin_amdgcn_s_barrier()
; #define PG8_SCHED __builtin_amdgcn_sched_barrier(0)
; template <class Epi, class Sched, bool ALIGN_EPI = false, bool SP2 = false>
; __device__ __forceinline__ void gemm_phase(PG8_LAS unsigned char* lds, const Gemm g, const Sched& S, const Epi& E) {
;     ...
;             PG8_LDB(B0, 0, 0); PG8_LDB(B1, 0, 1); PG8_SCHED; PG8_LDA(At, 0, 0); PG8_STAGE(PG8_SA(1, 1), a1 + hstep, voffA);
;             PG8_WAIT_V(8); PG8_WAIT_L(0); PG8_BAR; PG8_MMA(0, 0, At, B0); PG8_MMA(0, 1, At, B1); PG8_BAR; PG8_SCHED;
;             PG8_LDA(At, 0, 1); PG8_STAGE(PG8_SB(0, 0), b2, voffB); PG8_STAGE(PG8_SB(0, 1), b2 + hstep, voffB); PG8_STAGE(PG8_SA(0, 0), a2, voffA);
;             PG8_WAIT_V(8); PG8_WAIT_L(0); PG8_BAR; PG8_MMA(1, 0, At, B0); PG8_MMA(1, 1, At, B1); PG8_BAR; PG8_SCHED;
.LBB0_115:
	s_add_u32 s6, s4, 0xfff80080
	s_addc_u32 s7, s5, -1
	s_add_i32 s53, 0, 0x10000
	s_cmp_eq_u32 s52, 28
	s_cselect_b32 s9, s21, s7
	s_cselect_b32 s8, s26, s6
	s_cselect_b32 s7, s19, s29
	s_cselect_b32 s6, s27, s28
	s_add_i32 s56, 0, 0x14000
	v_add_u32_e32 v142, s53, v162
	v_add_u32_e32 v156, s56, v162
	ds_read_b128 v[130:133], v142
	ds_read_b128 v[134:137], v142 offset:1024
	ds_read_b128 v[138:141], v142 offset:2048
	ds_read_b128 v[142:145], v142 offset:3072
	ds_read_b128 v[178:181], v156
	ds_read_b128 v[182:185], v156 offset:1024
	ds_read_b128 v[200:203], v156 offset:2048
	ds_read_b128 v[204:207], v156 offset:3072
	s_add_i32 m0, s34, 0xc000
	ds_read_b128 v[208:211], v176
	ds_read_b128 v[212:215], v176 offset:1024
	ds_read_b128 v[216:219], v176 offset:2048
	ds_read_b128 v[220:223], v176 offset:3072
	ds_read_b128 v[224:227], v176 offset:4096
	ds_read_b128 v[228:231], v176 offset:5120
	ds_read_b128 v[232:235], v176 offset:6144
	ds_read_b128 v[236:239], v176 offset:7168
	global_load_lds_dwordx4 v152, s[4:5]
	s_add_i32 m0, s34, 0xe000
	s_nop 0
	global_load_lds_dwordx4 v154, s[4:5]
	s_waitcnt vmcnt(8)
	s_waitcnt lgkmcnt(0)
	s_barrier
	s_setprio 1
	s_waitcnt lgkmcnt(0)
	v_mfma_f32_16x16x32_bf16 v[126:129], v[130:133], v[208:211], v[126:129]
	v_mfma_f32_16x16x32_bf16 v[122:125], v[138:141], v[208:211], v[122:125]
	v_mfma_f32_16x16x32_bf16 v[118:121], v[130:133], v[216:219], v[118:121]
	v_mfma_f32_16x16x32_bf16 v[110:113], v[138:141], v[216:219], v[110:113]
	v_mfma_f32_16x16x32_bf16 v[102:105], v[130:133], v[224:227], v[102:105]
	v_mfma_f32_16x16x32_bf16 v[94:97], v[138:141], v[224:227], v[94:97]
	v_mfma_f32_16x16x32_bf16 v[86:89], v[130:133], v[232:235], v[86:89]
	v_mfma_f32_16x16x32_bf16 v[78:81], v[138:141], v[232:235], v[78:81]
	v_mfma_f32_16x16x32_bf16 v[126:129], v[134:137], v[212:215], v[126:129]
	v_mfma_f32_16x16x32_bf16 v[122:125], v[142:145], v[212:215], v[122:125]
	v_mfma_f32_16x16x32_bf16 v[118:121], v[134:137], v[220:223], v[118:121]
	v_mfma_f32_16x16x32_bf16 v[110:113], v[142:145], v[220:223], v[110:113]
	v_mfma_f32_16x16x32_bf16 v[102:105], v[134:137], v[228:231], v[102:105]
	v_mfma_f32_16x16x32_bf16 v[94:97], v[142:145], v[228:231], v[94:97]
	v_mfma_f32_16x16x32_bf16 v[86:89], v[134:137], v[236:239], v[86:89]
	v_mfma_f32_16x16x32_bf16 v[78:81], v[142:145], v[236:239], v[78:81]
	s_setprio 0
	s_setprio 1
	v_mfma_f32_16x16x32_bf16 v[114:117], v[178:181], v[208:211], v[114:117]
	v_mfma_f32_16x16x32_bf16 v[106:109], v[200:203], v[208:211], v[106:109]
	v_mfma_f32_16x16x32_bf16 v[98:101], v[178:181], v[216:219], v[98:101]
	v_mfma_f32_16x16x32_bf16 v[90:93], v[200:203], v[216:219], v[90:93]
	v_mfma_f32_16x16x32_bf16 v[82:85], v[178:181], v[224:227], v[82:85]
	v_mfma_f32_16x16x32_bf16 v[74:77], v[200:203], v[224:227], v[74:77]
	v_mfma_f32_16x16x32_bf16 v[70:73], v[178:181], v[232:235], v[70:73]
	v_mfma_f32_16x16x32_bf16 v[66:69], v[200:203], v[232:235], v[66:69]
	v_mfma_f32_16x16x32_bf16 v[114:117], v[182:185], v[212:215], v[114:117]
	v_mfma_f32_16x16x32_bf16 v[106:109], v[204:207], v[212:215], v[106:109]
	v_mfma_f32_16x16x32_bf16 v[98:101], v[182:185], v[220:223], v[98:101]
	v_mfma_f32_16x16x32_bf16 v[90:93], v[204:207], v[220:223], v[90:93]
	v_mfma_f32_16x16x32_bf16 v[82:85], v[182:185], v[228:231], v[82:85]
	v_mfma_f32_16x16x32_bf16 v[74:77], v[204:207], v[228:231], v[74:77]
	v_mfma_f32_16x16x32_bf16 v[70:73], v[182:185], v[236:239], v[70:73]
	v_mfma_f32_16x16x32_bf16 v[66:69], v[204:207], v[236:239], v[66:69]
	s_setprio 0
	s_barrier
	s_add_i32 s53, s53, s33
	s_add_u32 s84, s6, s44
	s_addc_u32 s85, s7, s45
	s_mov_b32 m0, s53
	ds_read_b128 v[208:211], v176 offset:16384
	ds_read_b128 v[212:215], v176 offset:17408
	ds_read_b128 v[216:219], v176 offset:18432
	ds_read_b128 v[220:223], v176 offset:19456
	ds_read_b128 v[224:227], v176 offset:20480
	ds_read_b128 v[228:231], v176 offset:21504
	ds_read_b128 v[232:235], v176 offset:22528
	ds_read_b128 v[236:239], v176 offset:23552
	global_load_lds_dwordx4 v0, s[6:7]
	s_add_i32 m0, s53, 0x2000
	s_add_u32 s54, s6, 0x80000
	s_addc_u32 s55, s7, 0
	s_add_i32 s53, s56, s33
	global_load_lds_dwordx4 v146, s[6:7]
	s_mov_b32 m0, s53
	s_nop 0
	global_load_lds_dwordx4 v0, s[54:55]
	s_add_i32 m0, s53, 0x2000
	s_nop 0
	global_load_lds_dwordx4 v146, s[54:55]
	s_add_u32 s86, s8, s44
	s_addc_u32 s87, s9, s45
	s_mov_b32 m0, s34
	s_nop 0
	global_load_lds_dwordx4 v150, s[8:9]
	s_mov_b32 m0, s35
	s_nop 0
	global_load_lds_dwordx4 v148, s[8:9]
	s_waitcnt vmcnt(8)
	s_waitcnt lgkmcnt(0)
	s_barrier
; #define PG8_STAGE(bufoff, gbase, voff) do { _Pragma("unroll") for (int _i = 0; _i < 2; ++_i) \
;         __builtin_amdgcn_global_load_lds((const unsigned*)((const char*)(gbase) + (voff)[_i]), (PG8_LAS unsigned*)(lds + (bufoff) + ldsw + _i * 8192), 16, 0, 0); } while (0)
; #define PG8_LDA(dst, b, h) do { _Pragma("unroll") for (int m = 0; m < 4; ++m) _Pragma("unroll") for (int k = 0; k < 2; ++k) dst[m][k] = *(const PG8_LAS bf16x8*)(lds + PG8_SA(b, h) + aoff + m * 2048 + k * 1024); } while (0)
; #define PG8_LDB(dst, b, h) do { _Pragma("unroll") for (int n = 0; n < 2; ++n) _Pragma("unroll") for (int k = 0; k < 2; ++k) dst[n][k] = *(const PG8_LAS bf16x8*)(lds + PG8_SB(b, h) + boff + n * 2048 + k * 1024); } while (0)
; #define PG8_MMA(ai, bj, At, Bt) do { __builtin_amdgcn_s_setprio(1); _Pragma("unroll") for (int m = 0; m < 4; ++m) _Pragma("unroll") for (int n = 0; n < 2; ++n) _Pragma("unroll") for (int k = 0; k < 2; ++k) \
;         acc[ai][bj][m][n] = __builtin_amdgcn_mfma_f32_16x16x32_bf16(Bt[n][k], At[m][k], acc[ai][bj][m][n], 0, 0, 0); __builtin_amdgcn_s_setprio(0); } while (0)
; #define PG8_WAIT_V(n) asm volatile("s_waitcnt vmcnt(" #n ")" ::: "memory")
; template <class Epi, class Sched, bool ALIGN_EPI = false, bool SP2 = false>
; __device__ __forceinline__ void gemm_phase(PG8_LAS unsigned char* lds, const Gemm g, const Sched& S, const Epi& E) {
;     ...
;             PG8_LDB(B0, 0, 0); PG8_LDB(B1, 0, 1); PG8_SCHED; PG8_LDA(At, 0, 0); PG8_STAGE(PG8_SA(1, 1), a1 + hstep, voffA);
;             PG8_WAIT_V(8); PG8_WAIT_L(0); PG8_BAR; PG8_MMA(0, 0, At, B0); PG8_MMA(0, 1, At, B1); PG8_BAR; PG8_SCHED;
;             PG8_LDA(At, 0, 1); PG8_STAGE(PG8_SB(0, 0), b2, voffB); PG8_STAGE(PG8_SB(0, 1), b2 + hstep, voffB); PG8_STAGE(PG8_SA(0, 0), a2, voffA);
;             PG8_WAIT_V(8); PG8_WAIT_L(0); PG8_BAR; PG8_MMA(1, 0, At, B0); PG8_MMA(1, 1, At, B1); PG8_BAR; PG8_SCHED;
;             PG8_LDB(B0, 1, 0); PG8_LDB(B1, 1, 1); PG8_SCHED; PG8_LDA(At, 1, 0); PG8_STAGE(PG8_SA(0, 1), a2 + hstep, voffA);
;             PG8_WAIT_V(8); PG8_WAIT_L(0); PG8_BAR; PG8_MMA(0, 0, At, B0); PG8_MMA(0, 1, At, B1); PG8_BAR; PG8_SCHED;
;             PG8_LDA(At, 1, 1); PG8_STAGE(PG8_SB(1, 0), b3, voffB); PG8_STAGE(PG8_SB(1, 1), b3 + hstep, voffB); PG8_STAGE(PG8_SA(1, 0), a3, voffA);
;             PG8_WAIT_V(8); PG8_WAIT_L(0); PG8_BAR; PG8_MMA(1, 0, At, B0); PG8_MMA(1, 1, At, B1); PG8_BAR; PG8_SCHED;
	s_setprio 1
	s_waitcnt lgkmcnt(0)
	v_mfma_f32_16x16x32_bf16 v[62:65], v[130:133], v[208:211], v[62:65]
	v_mfma_f32_16x16x32_bf16 v[58:61], v[138:141], v[208:211], v[58:61]
	v_mfma_f32_16x16x32_bf16 v[54:57], v[130:133], v[216:219], v[54:57]
	v_mfma_f32_16x16x32_bf16 v[46:49], v[138:141], v[216:219], v[46:49]
	v_mfma_f32_16x16x32_bf16 v[38:41], v[130:133], v[224:227], v[38:41]
	v_mfma_f32_16x16x32_bf16 v[30:33], v[138:141], v[224:227], v[30:33]
	v_mfma_f32_16x16x32_bf16 v[22:25], v[130:133], v[232:235], v[22:25]
	v_mfma_f32_16x16x32_bf16 v[14:17], v[138:141], v[232:235], v[14:17]
	v_mfma_f32_16x16x32_bf16 v[62:65], v[134:137], v[212:215], v[62:65]
	v_mfma_f32_16x16x32_bf16 v[58:61], v[142:145], v[212:215], v[58:61]
	v_mfma_f32_16x16x32_bf16 v[54:57], v[134:137], v[220:223], v[54:57]
	v_mfma_f32_16x16x32_bf16 v[46:49], v[142:145], v[220:223], v[46:49]
	v_mfma_f32_16x16x32_bf16 v[38:41], v[134:137], v[228:231], v[38:41]
	v_mfma_f32_16x16x32_bf16 v[30:33], v[142:145], v[228:231], v[30:33]
	v_mfma_f32_16x16x32_bf16 v[22:25], v[134:137], v[236:239], v[22:25]
	v_mfma_f32_16x16x32_bf16 v[14:17], v[142:145], v[236:239], v[14:17]
	s_setprio 0
	s_setprio 1
	v_mfma_f32_16x16x32_bf16 v[50:53], v[178:181], v[208:211], v[50:53]
	v_mfma_f32_16x16x32_bf16 v[42:45], v[200:203], v[208:211], v[42:45]
	v_mfma_f32_16x16x32_bf16 v[34:37], v[178:181], v[216:219], v[34:37]
	v_mfma_f32_16x16x32_bf16 v[26:29], v[200:203], v[216:219], v[26:29]
	v_mfma_f32_16x16x32_bf16 v[18:21], v[178:181], v[224:227], v[18:21]
	v_mfma_f32_16x16x32_bf16 v[10:13], v[200:203], v[224:227], v[10:13]
	v_mfma_f32_16x16x32_bf16 v[6:9], v[178:181], v[232:235], v[6:9]
	v_mfma_f32_16x16x32_bf16 v[2:5], v[200:203], v[232:235], v[2:5]
	v_mfma_f32_16x16x32_bf16 v[50:53], v[182:185], v[212:215], v[50:53]
	v_mfma_f32_16x16x32_bf16 v[42:45], v[204:207], v[212:215], v[42:45]
	v_mfma_f32_16x16x32_bf16 v[34:37], v[182:185], v[220:223], v[34:37]
	v_mfma_f32_16x16x32_bf16 v[26:29], v[204:207], v[220:223], v[26:29]
	v_mfma_f32_16x16x32_bf16 v[18:21], v[182:185], v[228:231], v[18:21]
	v_mfma_f32_16x16x32_bf16 v[10:13], v[204:207], v[228:231], v[10:13]
	v_mfma_f32_16x16x32_bf16 v[6:9], v[182:185], v[236:239], v[6:9]
	v_mfma_f32_16x16x32_bf16 v[2:5], v[204:207], v[236:239], v[2:5]
	s_setprio 0
	s_barrier
	s_add_i32 s53, 0, 0x18000
	s_add_i32 s54, 0, 0x1c000
	v_add_u32_e32 v142, s53, v162
	v_add_u32_e32 v158, s54, v162
	ds_read_b128 v[130:133], v142
	ds_read_b128 v[134:137], v142 offset:1024
	ds_read_b128 v[138:141], v142 offset:2048
	ds_read_b128 v[142:145], v142 offset:3072
	ds_read_b128 v[178:181], v158
	ds_read_b128 v[182:185], v158 offset:1024
	ds_read_b128 v[200:203], v158 offset:2048
	ds_read_b128 v[204:207], v158 offset:3072
	s_add_u32 s8, s8, 0x80000
	s_addc_u32 s9, s9, 0
	s_mov_b32 m0, s36
	ds_read_b128 v[208:211], v176 offset:32768
	ds_read_b128 v[212:215], v176 offset:33792
	ds_read_b128 v[216:219], v176 offset:34816
	ds_read_b128 v[220:223], v176 offset:35840
	ds_read_b128 v[224:227], v176 offset:36864
	ds_read_b128 v[228:231], v176 offset:37888
	ds_read_b128 v[232:235], v176 offset:38912
	ds_read_b128 v[236:239], v176 offset:39936
	global_load_lds_dwordx4 v150, s[8:9]
	s_mov_b32 m0, s37
	s_nop 0
	global_load_lds_dwordx4 v148, s[8:9]
	s_waitcnt vmcnt(8)
	s_waitcnt lgkmcnt(0)
	s_barrier
	s_setprio 1
	s_waitcnt lgkmcnt(0)
	v_mfma_f32_16x16x32_bf16 v[126:129], v[130:133], v[208:211], v[126:129]
	v_mfma_f32_16x16x32_bf16 v[122:125], v[138:141], v[208:211], v[122:125]
	v_mfma_f32_16x16x32_bf16 v[118:121], v[130:133], v[216:219], v[118:121]
	v_mfma_f32_16x16x32_bf16 v[110:113], v[138:141], v[216:219], v[110:113]
	v_mfma_f32_16x16x32_bf16 v[102:105], v[130:133], v[224:227], v[102:105]
	v_mfma_f32_16x16x32_bf16 v[94:97], v[138:141], v[224:227], v[94:97]
	v_mfma_f32_16x16x32_bf16 v[86:89], v[130:133], v[232:235], v[86:89]
	v_mfma_f32_16x16x32_bf16 v[78:81], v[138:141], v[232:235], v[78:81]
	v_mfma_f32_16x16x32_bf16 v[126:129], v[134:137], v[212:215], v[126:129]
	v_mfma_f32_16x16x32_bf16 v[122:125], v[142:145], v[212:215], v[122:125]
	v_mfma_f32_16x16x32_bf16 v[118:121], v[134:137], v[220:223], v[118:121]
	v_mfma_f32_16x16x32_bf16 v[110:113], v[142:145], v[220:223], v[110:113]
	v_mfma_f32_16x16x32_bf16 v[102:105], v[134:137], v[228:231], v[102:105]
	v_mfma_f32_16x16x32_bf16 v[94:97], v[142:145], v[228:231], v[94:97]
	v_mfma_f32_16x16x32_bf16 v[86:89], v[134:137], v[236:239], v[86:89]
	v_mfma_f32_16x16x32_bf16 v[78:81], v[142:145], v[236:239], v[78:81]
	s_setprio 0
	s_setprio 1
	v_mfma_f32_16x16x32_bf16 v[114:117], v[178:181], v[208:211], v[114:117]
	v_mfma_f32_16x16x32_bf16 v[106:109], v[200:203], v[208:211], v[106:109]
	v_mfma_f32_16x16x32_bf16 v[98:101], v[178:181], v[216:219], v[98:101]
	v_mfma_f32_16x16x32_bf16 v[90:93], v[200:203], v[216:219], v[90:93]
	v_mfma_f32_16x16x32_bf16 v[82:85], v[178:181], v[224:227], v[82:85]
	v_mfma_f32_16x16x32_bf16 v[74:77], v[200:203], v[224:227], v[74:77]
	v_mfma_f32_16x16x32_bf16 v[70:73], v[178:181], v[232:235], v[70:73]
	v_mfma_f32_16x16x32_bf16 v[66:69], v[200:203], v[232:235], v[66:69]
	v_mfma_f32_16x16x32_bf16 v[114:117], v[182:185], v[212:215], v[114:117]
	v_mfma_f32_16x16x32_bf16 v[106:109], v[204:207], v[212:215], v[106:109]
	v_mfma_f32_16x16x32_bf16 v[98:101], v[182:185], v[220:223], v[98:101]
	v_mfma_f32_16x16x32_bf16 v[90:93], v[204:207], v[220:223], v[90:93]
	v_mfma_f32_16x16x32_bf16 v[82:85], v[182:185], v[228:231], v[82:85]
	v_mfma_f32_16x16x32_bf16 v[74:77], v[204:207], v[228:231], v[74:77]
	v_mfma_f32_16x16x32_bf16 v[70:73], v[182:185], v[236:239], v[70:73]
	v_mfma_f32_16x16x32_bf16 v[66:69], v[204:207], v[236:239], v[66:69]
	s_setprio 0
	s_barrier
; #define PG8_STAGE(bufoff, gbase, voff) do { _Pragma("unroll") for (int _i = 0; _i < 2; ++_i) \
;         __builtin_amdgcn_global_load_lds((const unsigned*)((const char*)(gbase) + (voff)[_i]), (PG8_LAS unsigned*)(lds + (bufoff) + ldsw + _i * 8192), 16, 0, 0); } while (0)
; #define PG8_LDA(dst, b, h) do { _Pragma("unroll") for (int m = 0; m < 4; ++m) _Pragma("unroll") for (int k = 0; k < 2; ++k) dst[m][k] = *(const PG8_LAS bf16x8*)(lds + PG8_SA(b, h) + aoff + m * 2048 + k * 1024); } while (0)
; #define PG8_LDB(dst, b, h) do { _Pragma("unroll") for (int n = 0; n < 2; ++n) _Pragma("unroll") for (int k = 0; k < 2; ++k) dst[n][k] = *(const PG8_LAS bf16x8*)(lds + PG8_SB(b, h) + boff + n * 2048 + k * 1024); } while (0)
; template <class Epi, class Sched, bool ALIGN_EPI = false, bool SP2 = false>
; __device__ __forceinline__ void gemm_phase(PG8_LAS unsigned char* lds, const Gemm g, const Sched& S, const Epi& E) {
;     ...
;         for (int t = 0; t < nt; t += 2) {
;             const bool last = (t == nt - 2);
;             const char* a1 = cA + (size_t)(t + 1) * kstep;
;             const char* a2 = last ? nA : cA + (size_t)(t + 2) * kstep; const char* b2 = last ? nB : cB + (size_t)(t + 2) * kstep;
;             const char* a3 = a2 + kstep; const char* b3 = b2 + kstep;
;             if (last && has_next) S.a_ready(nxt);
;             if constexpr (SP2) {
;             PG8_LDB(B0, 0, 0); PG8_LDB(B1, 0, 1); PG8_SCHED; PG8_LDA(At, 0, 0); PG8_STAGE(PG8_SA(1, 1), a1 + hstep, voffA);
;             PG8_WAIT_V(8); PG8_WAIT_L(0); PG8_BAR; PG8_MMA(0, 0, At, B0); PG8_MMA(0, 1, At, B1); PG8_BAR; PG8_SCHED;
;             PG8_LDA(At, 0, 1); PG8_STAGE(PG8_SB(0, 0), b2, voffB); PG8_STAGE(PG8_SB(0, 1), b2 + hstep, voffB); PG8_STAGE(PG8_SA(0, 0), a2, voffA);
;             PG8_WAIT_V(8); PG8_WAIT_L(0); PG8_BAR; PG8_MMA(1, 0, At, B0); PG8_MMA(1, 1, At, B1); PG8_BAR; PG8_SCHED;
;             PG8_LDB(B0, 1, 0); PG8_LDB(B1, 1, 1); PG8_SCHED; PG8_LDA(At, 1, 0); PG8_STAGE(PG8_SA(0, 1), a2 + hstep, voffA);
;             PG8_WAIT_V(8); PG8_WAIT_L(0); PG8_BAR; PG8_MMA(0, 0, At, B0); PG8_MMA(0, 1, At, B1); PG8_BAR; PG8_SCHED;
;             PG8_LDA(At, 1, 1); PG8_STAGE(PG8_SB(1, 0), b3, voffB); PG8_STAGE(PG8_SB(1, 1), b3 + hstep, voffB); PG8_STAGE(PG8_SA(1, 0), a3, voffA);
;             PG8_WAIT_V(8); PG8_WAIT_L(0); PG8_BAR; PG8_MMA(1, 0, At, B0); PG8_MMA(1, 1, At, B1); PG8_BAR; PG8_SCHED;
	s_add_i32 s8, s53, s33
	s_mov_b32 m0, s8
	ds_read_b128 v[208:211], v176 offset:49152
	ds_read_b128 v[212:215], v176 offset:50176
	ds_read_b128 v[216:219], v176 offset:51200
	ds_read_b128 v[220:223], v176 offset:52224
	ds_read_b128 v[224:227], v176 offset:53248
	ds_read_b128 v[228:231], v176 offset:54272
	ds_read_b128 v[232:235], v176 offset:55296
	ds_read_b128 v[236:239], v176 offset:56320
	global_load_lds_dwordx4 v0, s[84:85]
	s_add_i32 m0, s8, 0x2000
	s_add_u32 s6, s6, 0x80080
	s_addc_u32 s7, s7, 0
	s_add_i32 s8, s54, s33
	global_load_lds_dwordx4 v146, s[84:85]
	s_mov_b32 m0, s8
	s_nop 0
	global_load_lds_dwordx4 v0, s[6:7]
	s_add_i32 m0, s8, 0x2000
	s_nop 0
	global_load_lds_dwordx4 v146, s[6:7]
	s_mov_b32 m0, s41
	s_nop 0
	global_load_lds_dwordx4 v150, s[86:87]
	s_mov_b32 m0, s42
	s_nop 0
	global_load_lds_dwordx4 v148, s[86:87]
	s_waitcnt vmcnt(8)
	s_waitcnt lgkmcnt(0)
	s_barrier
	s_setprio 1
	s_waitcnt lgkmcnt(0)
	v_mfma_f32_16x16x32_bf16 v[62:65], v[130:133], v[208:211], v[62:65]
	v_mfma_f32_16x16x32_bf16 v[58:61], v[138:141], v[208:211], v[58:61]
	v_mfma_f32_16x16x32_bf16 v[54:57], v[130:133], v[216:219], v[54:57]
	v_mfma_f32_16x16x32_bf16 v[46:49], v[138:141], v[216:219], v[46:49]
	v_mfma_f32_16x16x32_bf16 v[38:41], v[130:133], v[224:227], v[38:41]
	v_mfma_f32_16x16x32_bf16 v[30:33], v[138:141], v[224:227], v[30:33]
	v_mfma_f32_16x16x32_bf16 v[22:25], v[130:133], v[232:235], v[22:25]
	v_mfma_f32_16x16x32_bf16 v[14:17], v[138:141], v[232:235], v[14:17]
	v_mfma_f32_16x16x32_bf16 v[62:65], v[134:137], v[212:215], v[62:65]
	v_mfma_f32_16x16x32_bf16 v[58:61], v[142:145], v[212:215], v[58:61]
	v_mfma_f32_16x16x32_bf16 v[54:57], v[134:137], v[220:223], v[54:57]
	v_mfma_f32_16x16x32_bf16 v[46:49], v[142:145], v[220:223], v[46:49]
	v_mfma_f32_16x16x32_bf16 v[38:41], v[134:137], v[228:231], v[38:41]
	v_mfma_f32_16x16x32_bf16 v[30:33], v[142:145], v[228:231], v[30:33]
	v_mfma_f32_16x16x32_bf16 v[22:25], v[134:137], v[236:239], v[22:25]
	v_mfma_f32_16x16x32_bf16 v[14:17], v[142:145], v[236:239], v[14:17]
	s_setprio 0
	s_setprio 1
	v_mfma_f32_16x16x32_bf16 v[50:53], v[178:181], v[208:211], v[50:53]
	v_mfma_f32_16x16x32_bf16 v[42:45], v[200:203], v[208:211], v[42:45]
	v_mfma_f32_16x16x32_bf16 v[34:37], v[178:181], v[216:219], v[34:37]
	v_mfma_f32_16x16x32_bf16 v[26:29], v[200:203], v[216:219], v[26:29]
	v_mfma_f32_16x16x32_bf16 v[18:21], v[178:181], v[224:227], v[18:21]
	v_mfma_f32_16x16x32_bf16 v[10:13], v[200:203], v[224:227], v[10:13]
	v_mfma_f32_16x16x32_bf16 v[6:9], v[178:181], v[232:235], v[6:9]
	v_mfma_f32_16x16x32_bf16 v[2:5], v[200:203], v[232:235], v[2:5]
	v_mfma_f32_16x16x32_bf16 v[50:53], v[182:185], v[212:215], v[50:53]
	v_mfma_f32_16x16x32_bf16 v[42:45], v[204:207], v[212:215], v[42:45]
	v_mfma_f32_16x16x32_bf16 v[34:37], v[182:185], v[220:223], v[34:37]
	v_mfma_f32_16x16x32_bf16 v[26:29], v[204:207], v[220:223], v[26:29]
	v_mfma_f32_16x16x32_bf16 v[18:21], v[182:185], v[228:231], v[18:21]
	v_mfma_f32_16x16x32_bf16 v[10:13], v[204:207], v[228:231], v[10:13]
	v_mfma_f32_16x16x32_bf16 v[6:9], v[182:185], v[236:239], v[6:9]
	v_mfma_f32_16x16x32_bf16 v[2:5], v[204:207], v[236:239], v[2:5]
	s_setprio 0
	s_barrier
	s_add_i32 s52, s52, 2
	s_add_u32 s4, s4, 0x100
	s_addc_u32 s5, s5, 0
	s_add_u32 s28, s28, 0x100
	s_addc_u32 s29, s29, 0
	s_cmp_gt_u32 s52, 29
	s_cbranch_scc0 .LBB0_115
	s_and_b64 vcc, exec, s[16:17]
	s_cbranch_vccz .LBB0_118
	s_barrier

;     __device__ bool next(int i, Unit& u) const { const int j = first + i * G; if (j >= count) return false; u.pm = j / nN; u.pn = j % nN; return true; }
; #define PG8_STAGE(bufoff, gbase, voff) do { _Pragma("unroll") for (int _i = 0; _i < 2; ++_i) \
;         __builtin_amdgcn_global_load_lds((const unsigned*)((const char*)(gbase) + (voff)[_i]), (PG8_LAS unsigned*)(lds + (bufoff) + ldsw + _i * 8192), 16, 0, 0); } while (0)
; #define PG8_WAIT_V(n) asm volatile("s_waitcnt vmcnt(" #n ")" ::: "memory")
; template <class Epi, class Sched, bool ALIGN_EPI = false, bool SP2 = false>
; __device__ __forceinline__ void gemm_phase(PG8_LAS unsigned char* lds, const Gemm g, const Sched& S, const Epi& E) {
;     ...
;         const bool has_next = S.next(ui + 1, nxt);
;         const char* nA = has_next ? (const char*)g.A + (size_t)nxt.pm * tstep : cA; const char* nB = has_next ? (const char*)g.Bt + (size_t)nxt.pn * tstep : cB;
;         for (int t = 0; t < nt; t += 2) {
;             const bool last = (t == nt - 2);
;             const char* a1 = cA + (size_t)(t + 1) * kstep;
;             const char* a2 = last ? nA : cA + (size_t)(t + 2) * kstep; const char* b2 = last ? nB : cB + (size_t)(t + 2) * kstep;
;             const char* a3 = a2 + kstep; const char* b3 = b2 + kstep;
;             if (last && has_next) S.a_ready(nxt);
;             if constexpr (SP2) {
;             PG8_LDB(B0, 0, 0); PG8_LDB(B1, 0, 1); PG8_SCHED; PG8_LDA(At, 0, 0); PG8_STAGE(PG8_SA(1, 1), a1 + hstep, voffA);
;             PG8_WAIT_V(8); PG8_WAIT_L(0); PG8_BAR; PG8_MMA(0, 0, At, B0); PG8_MMA(0, 1, At, B1); PG8_BAR; PG8_SCHED;
;             PG8_LDA(At, 0, 1); PG8_STAGE(PG8_SB(0, 0), b2, voffB); PG8_STAGE(PG8_SB(0, 1), b2 + hstep, voffB); PG8_STAGE(PG8_SA(0, 0), a2, voffA);
;             PG8_WAIT_V(8); PG8_WAIT_L(0); PG8_BAR; PG8_MMA(1, 0, At, B0); PG8_MMA(1, 1, At, B1); PG8_BAR; PG8_SCHED;
;             PG8_LDB(B0, 1, 0); PG8_LDB(B1, 1, 1); PG8_SCHED; PG8_LDA(At, 1, 0); PG8_STAGE(PG8_SA(0, 1), a2 + hstep, voffA);
;             PG8_WAIT_V(8); PG8_WAIT_L(0); PG8_BAR; PG8_MMA(0, 0, At, B0); PG8_MMA(0, 1, At, B1); PG8_BAR; PG8_SCHED;
;             PG8_LDA(At, 1, 1); PG8_STAGE(PG8_SB(1, 0), b3, voffB); PG8_STAGE(PG8_SB(1, 1), b3 + hstep, voffB); PG8_STAGE(PG8_SA(1, 0), a3, voffA);
;             PG8_WAIT_V(8); PG8_WAIT_L(0); PG8_BAR; PG8_MMA(1, 0, At, B0); PG8_MMA(1, 1, At, B1); PG8_BAR; PG8_SCHED;
.LBB0_826:
	s_add_u32 s16, s4, s14
	s_addc_u32 s17, s5, s15
	s_add_u32 s16, s16, 0x100
	s_addc_u32 s17, s17, 0
	s_add_u32 s48, s41, s14
	s_addc_u32 s49, s42, s15
	s_add_i32 s50, 0, 0x10000
	s_cmpk_eq_i32 s14, 0xf00
	s_cselect_b32 s19, s9, s17
	s_cselect_b32 s18, s43, s16
	v_add_u32_e32 v160, s50, v144
	s_cselect_b32 s17, s7, s49
	s_cselect_b32 s16, s46, s48
	s_add_i32 s51, 0, 0x14000
	ds_read_b128 v[146:149], v160
	ds_read_b128 v[150:153], v160 offset:1024
	ds_read_b128 v[156:159], v160 offset:2048
	ds_read_b128 v[180:183], v160 offset:3072
	v_add_u32_e32 v160, s51, v144
	ds_read_b128 v[200:203], v160
	ds_read_b128 v[204:207], v160 offset:1024
	ds_read_b128 v[208:211], v160 offset:2048
	ds_read_b128 v[212:215], v160 offset:3072
	v_lshl_add_u64 v[160:161], v[140:141], 0, s[14:15]
	s_add_i32 m0, s30, 0xc000
	ds_read_b128 v[216:219], v145
	ds_read_b128 v[220:223], v145 offset:1024
	ds_read_b128 v[224:227], v145 offset:2048
	ds_read_b128 v[228:231], v145 offset:3072
	ds_read_b128 v[232:235], v145 offset:4096
	ds_read_b128 v[236:239], v145 offset:5120
	ds_read_b128 v[240:243], v145 offset:6144
	ds_read_b128 v[244:247], v145 offset:7168
	global_load_lds_dwordx4 v[160:161], off
	v_lshl_add_u64 v[160:161], v[142:143], 0, s[14:15]
	s_add_i32 m0, s30, 0xe000
	s_nop 0
	global_load_lds_dwordx4 v[160:161], off
	s_waitcnt vmcnt(8)
	s_waitcnt lgkmcnt(0)
	s_barrier
	s_setprio 1
	s_waitcnt lgkmcnt(0)
	v_mfma_f32_16x16x32_bf16 v[126:129], v[146:149], v[216:219], v[126:129]
	v_mfma_f32_16x16x32_bf16 v[122:125], v[156:159], v[216:219], v[122:125]
	v_mfma_f32_16x16x32_bf16 v[110:113], v[146:149], v[224:227], v[110:113]
	v_mfma_f32_16x16x32_bf16 v[106:109], v[156:159], v[224:227], v[106:109]
	v_mfma_f32_16x16x32_bf16 v[94:97], v[146:149], v[232:235], v[94:97]
	v_mfma_f32_16x16x32_bf16 v[90:93], v[156:159], v[232:235], v[90:93]
	v_mfma_f32_16x16x32_bf16 v[78:81], v[146:149], v[240:243], v[78:81]
	v_mfma_f32_16x16x32_bf16 v[74:77], v[156:159], v[240:243], v[74:77]
	v_mfma_f32_16x16x32_bf16 v[126:129], v[150:153], v[220:223], v[126:129]
	v_mfma_f32_16x16x32_bf16 v[122:125], v[180:183], v[220:223], v[122:125]
	v_mfma_f32_16x16x32_bf16 v[110:113], v[150:153], v[228:231], v[110:113]
	v_mfma_f32_16x16x32_bf16 v[106:109], v[180:183], v[228:231], v[106:109]
	v_mfma_f32_16x16x32_bf16 v[94:97], v[150:153], v[236:239], v[94:97]
	v_mfma_f32_16x16x32_bf16 v[90:93], v[180:183], v[236:239], v[90:93]
	v_mfma_f32_16x16x32_bf16 v[78:81], v[150:153], v[244:247], v[78:81]
	v_mfma_f32_16x16x32_bf16 v[74:77], v[180:183], v[244:247], v[74:77]
	s_setprio 0
	s_setprio 1
	v_mfma_f32_16x16x32_bf16 v[118:121], v[200:203], v[216:219], v[118:121]
	v_mfma_f32_16x16x32_bf16 v[114:117], v[208:211], v[216:219], v[114:117]
	v_mfma_f32_16x16x32_bf16 v[102:105], v[200:203], v[224:227], v[102:105]
	v_mfma_f32_16x16x32_bf16 v[98:101], v[208:211], v[224:227], v[98:101]
	v_mfma_f32_16x16x32_bf16 v[86:89], v[200:203], v[232:235], v[86:89]
	v_mfma_f32_16x16x32_bf16 v[82:85], v[208:211], v[232:235], v[82:85]
	v_mfma_f32_16x16x32_bf16 v[70:73], v[200:203], v[240:243], v[70:73]
	v_mfma_f32_16x16x32_bf16 v[66:69], v[208:211], v[240:243], v[66:69]
	v_mfma_f32_16x16x32_bf16 v[118:121], v[204:207], v[220:223], v[118:121]
	v_mfma_f32_16x16x32_bf16 v[114:117], v[212:215], v[220:223], v[114:117]
	v_mfma_f32_16x16x32_bf16 v[102:105], v[204:207], v[228:231], v[102:105]
	v_mfma_f32_16x16x32_bf16 v[98:101], v[212:215], v[228:231], v[98:101]
	v_mfma_f32_16x16x32_bf16 v[86:89], v[204:207], v[236:239], v[86:89]
	v_mfma_f32_16x16x32_bf16 v[82:85], v[212:215], v[236:239], v[82:85]
	v_mfma_f32_16x16x32_bf16 v[70:73], v[204:207], v[244:247], v[70:73]
	v_mfma_f32_16x16x32_bf16 v[66:69], v[212:215], v[244:247], v[66:69]
	s_setprio 0
	s_barrier
	s_add_i32 s48, s50, s29
	s_add_u32 s84, s16, s44
	s_addc_u32 s85, s17, s45
	s_mov_b32 m0, s48
	ds_read_b128 v[216:219], v145 offset:16384
	ds_read_b128 v[220:223], v145 offset:17408
	ds_read_b128 v[224:227], v145 offset:18432
	ds_read_b128 v[228:231], v145 offset:19456
	ds_read_b128 v[232:235], v145 offset:20480
	ds_read_b128 v[236:239], v145 offset:21504
	ds_read_b128 v[240:243], v145 offset:22528
	ds_read_b128 v[244:247], v145 offset:23552
	global_load_lds_dwordx4 v0, s[16:17]
	s_add_i32 m0, s48, 0x2000
	s_add_u32 s48, s16, 0x80000
	s_addc_u32 s49, s17, 0
	s_add_i32 s50, s51, s29
	global_load_lds_dwordx4 v130, s[16:17]
	s_mov_b32 m0, s50
	s_nop 0
	global_load_lds_dwordx4 v0, s[48:49]
	s_add_i32 m0, s50, 0x2000
	s_nop 0
	global_load_lds_dwordx4 v130, s[48:49]
	s_add_u32 s86, s18, s44
	s_addc_u32 s87, s19, s45
	s_mov_b32 m0, s30
	s_nop 0
	global_load_lds_dwordx4 v134, s[18:19]
	s_mov_b32 m0, s31
	s_nop 0
	global_load_lds_dwordx4 v132, s[18:19]
	s_waitcnt vmcnt(8)
	s_waitcnt lgkmcnt(0)
	s_barrier
; #define PG8_STAGE(bufoff, gbase, voff) do { _Pragma("unroll") for (int _i = 0; _i < 2; ++_i) \
;         __builtin_amdgcn_global_load_lds((const unsigned*)((const char*)(gbase) + (voff)[_i]), (PG8_LAS unsigned*)(lds + (bufoff) + ldsw + _i * 8192), 16, 0, 0); } while (0)
; #define PG8_LDA(dst, b, h) do { _Pragma("unroll") for (int m = 0; m < 4; ++m) _Pragma("unroll") for (int k = 0; k < 2; ++k) dst[m][k] = *(const PG8_LAS bf16x8*)(lds + PG8_SA(b, h) + aoff + m * 2048 + k * 1024); } while (0)
; #define PG8_LDB(dst, b, h) do { _Pragma("unroll") for (int n = 0; n < 2; ++n) _Pragma("unroll") for (int k = 0; k < 2; ++k) dst[n][k] = *(const PG8_LAS bf16x8*)(lds + PG8_SB(b, h) + boff + n * 2048 + k * 1024); } while (0)
; #define PG8_MMA(ai, bj, At, Bt) do { __builtin_amdgcn_s_setprio(1); _Pragma("unroll") for (int m = 0; m < 4; ++m) _Pragma("unroll") for (int n = 0; n < 2; ++n) _Pragma("unroll") for (int k = 0; k < 2; ++k) \
;         acc[ai][bj][m][n] = __builtin_amdgcn_mfma_f32_16x16x32_bf16(Bt[n][k], At[m][k], acc[ai][bj][m][n], 0, 0, 0); __builtin_amdgcn_s_setprio(0); } while (0)
; #define PG8_WAIT_V(n) asm volatile("s_waitcnt vmcnt(" #n ")" ::: "memory")
; template <class Epi, class Sched, bool ALIGN_EPI = false, bool SP2 = false>
; __device__ __forceinline__ void gemm_phase(PG8_LAS unsigned char* lds, const Gemm g, const Sched& S, const Epi& E) {
;     ...
;             PG8_LDB(B0, 0, 0); PG8_LDB(B1, 0, 1); PG8_SCHED; PG8_LDA(At, 0, 0); PG8_STAGE(PG8_SA(1, 1), a1 + hstep, voffA);
;             PG8_WAIT_V(8); PG8_WAIT_L(0); PG8_BAR; PG8_MMA(0, 0, At, B0); PG8_MMA(0, 1, At, B1); PG8_BAR; PG8_SCHED;
;             PG8_LDA(At, 0, 1); PG8_STAGE(PG8_SB(0, 0), b2, voffB); PG8_STAGE(PG8_SB(0, 1), b2 + hstep, voffB); PG8_STAGE(PG8_SA(0, 0), a2, voffA);
;             PG8_WAIT_V(8); PG8_WAIT_L(0); PG8_BAR; PG8_MMA(1, 0, At, B0); PG8_MMA(1, 1, At, B1); PG8_BAR; PG8_SCHED;
;             PG8_LDB(B0, 1, 0); PG8_LDB(B1, 1, 1); PG8_SCHED; PG8_LDA(At, 1, 0); PG8_STAGE(PG8_SA(0, 1), a2 + hstep, voffA);
;             PG8_WAIT_V(8); PG8_WAIT_L(0); PG8_BAR; PG8_MMA(0, 0, At, B0); PG8_MMA(0, 1, At, B1); PG8_BAR; PG8_SCHED;
;             PG8_LDA(At, 1, 1); PG8_STAGE(PG8_SB(1, 0), b3, voffB); PG8_STAGE(PG8_SB(1, 1), b3 + hstep, voffB); PG8_STAGE(PG8_SA(1, 0), a3, voffA);
;             PG8_WAIT_V(8); PG8_WAIT_L(0); PG8_BAR; PG8_MMA(1, 0, At, B0); PG8_MMA(1, 1, At, B1); PG8_BAR; PG8_SCHED;
	s_setprio 1
	s_waitcnt lgkmcnt(0)
	v_mfma_f32_16x16x32_bf16 v[62:65], v[146:149], v[216:219], v[62:65]
	v_mfma_f32_16x16x32_bf16 v[58:61], v[156:159], v[216:219], v[58:61]
	v_mfma_f32_16x16x32_bf16 v[46:49], v[146:149], v[224:227], v[46:49]
	v_mfma_f32_16x16x32_bf16 v[42:45], v[156:159], v[224:227], v[42:45]
	v_mfma_f32_16x16x32_bf16 v[30:33], v[146:149], v[232:235], v[30:33]
	v_mfma_f32_16x16x32_bf16 v[26:29], v[156:159], v[232:235], v[26:29]
	v_mfma_f32_16x16x32_bf16 v[14:17], v[146:149], v[240:243], v[14:17]
	v_mfma_f32_16x16x32_bf16 v[10:13], v[156:159], v[240:243], v[10:13]
	v_mfma_f32_16x16x32_bf16 v[62:65], v[150:153], v[220:223], v[62:65]
	v_mfma_f32_16x16x32_bf16 v[58:61], v[180:183], v[220:223], v[58:61]
	v_mfma_f32_16x16x32_bf16 v[46:49], v[150:153], v[228:231], v[46:49]
	v_mfma_f32_16x16x32_bf16 v[42:45], v[180:183], v[228:231], v[42:45]
	v_mfma_f32_16x16x32_bf16 v[30:33], v[150:153], v[236:239], v[30:33]
	v_mfma_f32_16x16x32_bf16 v[26:29], v[180:183], v[236:239], v[26:29]
	v_mfma_f32_16x16x32_bf16 v[14:17], v[150:153], v[244:247], v[14:17]
	v_mfma_f32_16x16x32_bf16 v[10:13], v[180:183], v[244:247], v[10:13]
	s_setprio 0
	s_setprio 1
	v_mfma_f32_16x16x32_bf16 v[54:57], v[200:203], v[216:219], v[54:57]
	v_mfma_f32_16x16x32_bf16 v[50:53], v[208:211], v[216:219], v[50:53]
	v_mfma_f32_16x16x32_bf16 v[38:41], v[200:203], v[224:227], v[38:41]
	v_mfma_f32_16x16x32_bf16 v[34:37], v[208:211], v[224:227], v[34:37]
	v_mfma_f32_16x16x32_bf16 v[22:25], v[200:203], v[232:235], v[22:25]
	v_mfma_f32_16x16x32_bf16 v[18:21], v[208:211], v[232:235], v[18:21]
	v_mfma_f32_16x16x32_bf16 v[6:9], v[200:203], v[240:243], v[6:9]
	v_mfma_f32_16x16x32_bf16 v[2:5], v[208:211], v[240:243], v[2:5]
	v_mfma_f32_16x16x32_bf16 v[54:57], v[204:207], v[220:223], v[54:57]
	v_mfma_f32_16x16x32_bf16 v[50:53], v[212:215], v[220:223], v[50:53]
	v_mfma_f32_16x16x32_bf16 v[38:41], v[204:207], v[228:231], v[38:41]
	v_mfma_f32_16x16x32_bf16 v[34:37], v[212:215], v[228:231], v[34:37]
	v_mfma_f32_16x16x32_bf16 v[22:25], v[204:207], v[236:239], v[22:25]
	v_mfma_f32_16x16x32_bf16 v[18:21], v[212:215], v[236:239], v[18:21]
	v_mfma_f32_16x16x32_bf16 v[6:9], v[204:207], v[244:247], v[6:9]
	v_mfma_f32_16x16x32_bf16 v[2:5], v[212:215], v[244:247], v[2:5]
	s_setprio 0
	s_barrier
	s_add_i32 s48, 0, 0x18000
	v_add_u32_e32 v162, s48, v144
	s_add_i32 s49, 0, 0x1c000
	ds_read_b128 v[146:149], v162
	ds_read_b128 v[150:153], v162 offset:1024
	ds_read_b128 v[156:159], v162 offset:2048
	ds_read_b128 v[180:183], v162 offset:3072
	v_add_u32_e32 v162, s49, v144
	ds_read_b128 v[200:203], v162
	ds_read_b128 v[204:207], v162 offset:1024
	ds_read_b128 v[208:211], v162 offset:2048
	ds_read_b128 v[212:215], v162 offset:3072
	s_add_u32 s18, s18, 0x80000
	s_addc_u32 s19, s19, 0
	s_mov_b32 m0, s33
	ds_read_b128 v[216:219], v145 offset:32768
	ds_read_b128 v[220:223], v145 offset:33792
	ds_read_b128 v[224:227], v145 offset:34816
	ds_read_b128 v[228:231], v145 offset:35840
	ds_read_b128 v[232:235], v145 offset:36864
	ds_read_b128 v[236:239], v145 offset:37888
	ds_read_b128 v[240:243], v145 offset:38912
	ds_read_b128 v[244:247], v145 offset:39936
	global_load_lds_dwordx4 v134, s[18:19]
	s_mov_b32 m0, s34
	s_nop 0
	global_load_lds_dwordx4 v132, s[18:19]
	s_waitcnt vmcnt(8)
	s_waitcnt lgkmcnt(0)
	s_barrier
	s_setprio 1
	s_waitcnt lgkmcnt(0)
	v_mfma_f32_16x16x32_bf16 v[126:129], v[146:149], v[216:219], v[126:129]
	v_mfma_f32_16x16x32_bf16 v[122:125], v[156:159], v[216:219], v[122:125]
	v_mfma_f32_16x16x32_bf16 v[110:113], v[146:149], v[224:227], v[110:113]
	v_mfma_f32_16x16x32_bf16 v[106:109], v[156:159], v[224:227], v[106:109]
	v_mfma_f32_16x16x32_bf16 v[94:97], v[146:149], v[232:235], v[94:97]
	v_mfma_f32_16x16x32_bf16 v[90:93], v[156:159], v[232:235], v[90:93]
	v_mfma_f32_16x16x32_bf16 v[78:81], v[146:149], v[240:243], v[78:81]
	v_mfma_f32_16x16x32_bf16 v[74:77], v[156:159], v[240:243], v[74:77]
	v_mfma_f32_16x16x32_bf16 v[126:129], v[150:153], v[220:223], v[126:129]
	v_mfma_f32_16x16x32_bf16 v[122:125], v[180:183], v[220:223], v[122:125]
	v_mfma_f32_16x16x32_bf16 v[110:113], v[150:153], v[228:231], v[110:113]
	v_mfma_f32_16x16x32_bf16 v[106:109], v[180:183], v[228:231], v[106:109]
	v_mfma_f32_16x16x32_bf16 v[94:97], v[150:153], v[236:239], v[94:97]
	v_mfma_f32_16x16x32_bf16 v[90:93], v[180:183], v[236:239], v[90:93]
	v_mfma_f32_16x16x32_bf16 v[78:81], v[150:153], v[244:247], v[78:81]
	v_mfma_f32_16x16x32_bf16 v[74:77], v[180:183], v[244:247], v[74:77]
	s_setprio 0
	s_setprio 1
	v_mfma_f32_16x16x32_bf16 v[118:121], v[200:203], v[216:219], v[118:121]
	v_mfma_f32_16x16x32_bf16 v[114:117], v[208:211], v[216:219], v[114:117]
	v_mfma_f32_16x16x32_bf16 v[102:105], v[200:203], v[224:227], v[102:105]
	v_mfma_f32_16x16x32_bf16 v[98:101], v[208:211], v[224:227], v[98:101]
	v_mfma_f32_16x16x32_bf16 v[86:89], v[200:203], v[232:235], v[86:89]
	v_mfma_f32_16x16x32_bf16 v[82:85], v[208:211], v[232:235], v[82:85]
	v_mfma_f32_16x16x32_bf16 v[70:73], v[200:203], v[240:243], v[70:73]
	v_mfma_f32_16x16x32_bf16 v[66:69], v[208:211], v[240:243], v[66:69]
	v_mfma_f32_16x16x32_bf16 v[118:121], v[204:207], v[220:223], v[118:121]
	v_mfma_f32_16x16x32_bf16 v[114:117], v[212:215], v[220:223], v[114:117]
	v_mfma_f32_16x16x32_bf16 v[102:105], v[204:207], v[228:231], v[102:105]
	v_mfma_f32_16x16x32_bf16 v[98:101], v[212:215], v[228:231], v[98:101]
	v_mfma_f32_16x16x32_bf16 v[86:89], v[204:207], v[236:239], v[86:89]
	v_mfma_f32_16x16x32_bf16 v[82:85], v[212:215], v[236:239], v[82:85]
	v_mfma_f32_16x16x32_bf16 v[70:73], v[204:207], v[244:247], v[70:73]
	v_mfma_f32_16x16x32_bf16 v[66:69], v[212:215], v[244:247], v[66:69]
	s_setprio 0
	s_barrier
; #define PG8_STAGE(bufoff, gbase, voff) do { _Pragma("unroll") for (int _i = 0; _i < 2; ++_i) \
;         __builtin_amdgcn_global_load_lds((const unsigned*)((const char*)(gbase) + (voff)[_i]), (PG8_LAS unsigned*)(lds + (bufoff) + ldsw + _i * 8192), 16, 0, 0); } while (0)
; #define PG8_LDA(dst, b, h) do { _Pragma("unroll") for (int m = 0; m < 4; ++m) _Pragma("unroll") for (int k = 0; k < 2; ++k) dst[m][k] = *(const PG8_LAS bf16x8*)(lds + PG8_SA(b, h) + aoff + m * 2048 + k * 1024); } while (0)
; #define PG8_LDB(dst, b, h) do { _Pragma("unroll") for (int n = 0; n < 2; ++n) _Pragma("unroll") for (int k = 0; k < 2; ++k) dst[n][k] = *(const PG8_LAS bf16x8*)(lds + PG8_SB(b, h) + boff + n * 2048 + k * 1024); } while (0)
; #define PG8_WAIT_V(n) asm volatile("s_waitcnt vmcnt(" #n ")" ::: "memory")
; template <class Epi, class Sched, bool ALIGN_EPI = false, bool SP2 = false>
; __device__ __forceinline__ void gemm_phase(PG8_LAS unsigned char* lds, const Gemm g, const Sched& S, const Epi& E) {
;     ...
;             PG8_LDB(B0, 0, 0); PG8_LDB(B1, 0, 1); PG8_SCHED; PG8_LDA(At, 0, 0); PG8_STAGE(PG8_SA(1, 1), a1 + hstep, voffA);
;             PG8_WAIT_V(8); PG8_WAIT_L(0); PG8_BAR; PG8_MMA(0, 0, At, B0); PG8_MMA(0, 1, At, B1); PG8_BAR; PG8_SCHED;
;             PG8_LDA(At, 0, 1); PG8_STAGE(PG8_SB(0, 0), b2, voffB); PG8_STAGE(PG8_SB(0, 1), b2 + hstep, voffB); PG8_STAGE(PG8_SA(0, 0), a2, voffA);
;             PG8_WAIT_V(8); PG8_WAIT_L(0); PG8_BAR; PG8_MMA(1, 0, At, B0); PG8_MMA(1, 1, At, B1); PG8_BAR; PG8_SCHED;
;             PG8_LDB(B0, 1, 0); PG8_LDB(B1, 1, 1); PG8_SCHED; PG8_LDA(At, 1, 0); PG8_STAGE(PG8_SA(0, 1), a2 + hstep, voffA);
;             PG8_WAIT_V(8); PG8_WAIT_L(0); PG8_BAR; PG8_MMA(0, 0, At, B0); PG8_MMA(0, 1, At, B1); PG8_BAR; PG8_SCHED;
;             PG8_LDA(At, 1, 1); PG8_STAGE(PG8_SB(1, 0), b3, voffB); PG8_STAGE(PG8_SB(1, 1), b3 + hstep, voffB); PG8_STAGE(PG8_SA(1, 0), a3, voffA);
;             PG8_WAIT_V(8); PG8_WAIT_L(0); PG8_BAR; PG8_MMA(1, 0, At, B0); PG8_MMA(1, 1, At, B1); PG8_BAR; PG8_SCHED;
;     ...
;         if (!has_next) break;
; #pragma unroll
;         for (int a = 0; a < 2; ++a)
; #pragma unroll
;             for (int b = 0; b < 2; ++b)
; #pragma unroll
;                 for (int m = 0; m < 4; ++m)
; #pragma unroll
;                     for (int n = 0; n < 2; ++n) acc[a][b][m][n] = (f32x4){0.f, 0.f, 0.f, 0.f};
;         cur = nxt; cA = nA; cB = nB; ++ui;
	s_add_i32 s18, s48, s29
	s_mov_b32 m0, s18
	ds_read_b128 v[216:219], v145 offset:49152
	ds_read_b128 v[220:223], v145 offset:50176
	ds_read_b128 v[224:227], v145 offset:51200
	ds_read_b128 v[228:231], v145 offset:52224
	ds_read_b128 v[232:235], v145 offset:53248
	ds_read_b128 v[236:239], v145 offset:54272
	ds_read_b128 v[240:243], v145 offset:55296
	ds_read_b128 v[244:247], v145 offset:56320
	global_load_lds_dwordx4 v0, s[84:85]
	s_add_i32 m0, s18, 0x2000
	s_add_u32 s16, s16, 0x80080
	s_addc_u32 s17, s17, 0
	s_add_i32 s18, s49, s29
	global_load_lds_dwordx4 v130, s[84:85]
	s_mov_b32 m0, s18
	s_nop 0
	global_load_lds_dwordx4 v0, s[16:17]
	s_add_i32 m0, s18, 0x2000
	s_nop 0
	global_load_lds_dwordx4 v130, s[16:17]
	s_mov_b32 m0, s35
	s_nop 0
	global_load_lds_dwordx4 v134, s[86:87]
	s_mov_b32 m0, s36
	s_nop 0
	global_load_lds_dwordx4 v132, s[86:87]
	s_waitcnt vmcnt(8)
	s_waitcnt lgkmcnt(0)
	s_barrier
	s_setprio 1
	s_waitcnt lgkmcnt(0)
	v_mfma_f32_16x16x32_bf16 v[62:65], v[146:149], v[216:219], v[62:65]
	v_mfma_f32_16x16x32_bf16 v[58:61], v[156:159], v[216:219], v[58:61]
	v_mfma_f32_16x16x32_bf16 v[46:49], v[146:149], v[224:227], v[46:49]
	v_mfma_f32_16x16x32_bf16 v[42:45], v[156:159], v[224:227], v[42:45]
	v_mfma_f32_16x16x32_bf16 v[30:33], v[146:149], v[232:235], v[30:33]
	v_mfma_f32_16x16x32_bf16 v[26:29], v[156:159], v[232:235], v[26:29]
	v_mfma_f32_16x16x32_bf16 v[14:17], v[146:149], v[240:243], v[14:17]
	v_mfma_f32_16x16x32_bf16 v[10:13], v[156:159], v[240:243], v[10:13]
	v_mfma_f32_16x16x32_bf16 v[62:65], v[150:153], v[220:223], v[62:65]
	v_mfma_f32_16x16x32_bf16 v[58:61], v[180:183], v[220:223], v[58:61]
	v_mfma_f32_16x16x32_bf16 v[46:49], v[150:153], v[228:231], v[46:49]
	v_mfma_f32_16x16x32_bf16 v[42:45], v[180:183], v[228:231], v[42:45]
	v_mfma_f32_16x16x32_bf16 v[30:33], v[150:153], v[236:239], v[30:33]
	v_mfma_f32_16x16x32_bf16 v[26:29], v[180:183], v[236:239], v[26:29]
	v_mfma_f32_16x16x32_bf16 v[14:17], v[150:153], v[244:247], v[14:17]
	v_mfma_f32_16x16x32_bf16 v[10:13], v[180:183], v[244:247], v[10:13]
	s_setprio 0
	s_setprio 1
	v_mfma_f32_16x16x32_bf16 v[54:57], v[200:203], v[216:219], v[54:57]
	v_mfma_f32_16x16x32_bf16 v[50:53], v[208:211], v[216:219], v[50:53]
	v_mfma_f32_16x16x32_bf16 v[38:41], v[200:203], v[224:227], v[38:41]
	v_mfma_f32_16x16x32_bf16 v[34:37], v[208:211], v[224:227], v[34:37]
	v_mfma_f32_16x16x32_bf16 v[22:25], v[200:203], v[232:235], v[22:25]
	v_mfma_f32_16x16x32_bf16 v[18:21], v[208:211], v[232:235], v[18:21]
	v_mfma_f32_16x16x32_bf16 v[6:9], v[200:203], v[240:243], v[6:9]
	v_mfma_f32_16x16x32_bf16 v[2:5], v[208:211], v[240:243], v[2:5]
	v_mfma_f32_16x16x32_bf16 v[54:57], v[204:207], v[220:223], v[54:57]
	v_mfma_f32_16x16x32_bf16 v[50:53], v[212:215], v[220:223], v[50:53]
	v_mfma_f32_16x16x32_bf16 v[38:41], v[204:207], v[228:231], v[38:41]
	v_mfma_f32_16x16x32_bf16 v[34:37], v[212:215], v[228:231], v[34:37]
	v_mfma_f32_16x16x32_bf16 v[22:25], v[204:207], v[236:239], v[22:25]
	v_mfma_f32_16x16x32_bf16 v[18:21], v[212:215], v[236:239], v[18:21]
	v_mfma_f32_16x16x32_bf16 v[6:9], v[204:207], v[244:247], v[6:9]
	v_mfma_f32_16x16x32_bf16 v[2:5], v[212:215], v[244:247], v[2:5]
	s_setprio 0
	s_barrier
	s_add_i32 s47, s47, 2
	s_add_u32 s14, s14, 0x100
	s_addc_u32 s15, s15, 0
	s_cmp_gt_u32 s47, 29
	s_cbranch_scc0 .LBB0_826
	s_add_u32 s14, s41, 0xffffff00
	s_addc_u32 s15, s42, -1
	s_andn2_b64 vcc, exec, s[2:3]
	s_cbranch_vccnz .LBB0_817
	v_mov_b32_e32 v2, 0
	s_mov_b32 s25, s6
	s_mov_b32 s24, s8
	s_mov_b64 s[4:5], s[12:13]
	s_mov_b32 s37, s40
	v_mov_b32_e32 v3, v2
	v_mov_b32_e32 v4, v2
	v_mov_b32_e32 v5, v2
	v_mov_b32_e32 v6, v2
	v_mov_b32_e32 v7, v2
	v_mov_b32_e32 v8, v2
	v_mov_b32_e32 v9, v2
	v_mov_b32_e32 v18, v2
	v_mov_b32_e32 v19, v2
	v_mov_b32_e32 v20, v2
	v_mov_b32_e32 v21, v2
	v_mov_b32_e32 v22, v2
	v_mov_b32_e32 v23, v2
	v_mov_b32_e32 v24, v2
	v_mov_b32_e32 v25, v2
	v_mov_b32_e32 v34, v2
	v_mov_b32_e32 v35, v2
	v_mov_b32_e32 v36, v2
	v_mov_b32_e32 v37, v2
	v_mov_b32_e32 v38, v2
	v_mov_b32_e32 v39, v2
	v_mov_b32_e32 v40, v2
	v_mov_b32_e32 v41, v2
	v_mov_b32_e32 v50, v2
	v_mov_b32_e32 v51, v2
	v_mov_b32_e32 v52, v2
	v_mov_b32_e32 v53, v2
	v_mov_b32_e32 v54, v2
	v_mov_b32_e32 v55, v2
	v_mov_b32_e32 v56, v2
	v_mov_b32_e32 v57, v2
	v_mov_b32_e32 v10, v2
	v_mov_b32_e32 v11, v2
	v_mov_b32_e32 v12, v2
	v_mov_b32_e32 v13, v2
	v_mov_b32_e32 v14, v2
	v_mov_b32_e32 v15, v2
	v_mov_b32_e32 v16, v2
	v_mov_b32_e32 v17, v2
	v_mov_b32_e32 v26, v2
	v_mov_b32_e32 v27, v2
	v_mov_b32_e32 v28, v2
	v_mov_b32_e32 v29, v2
	v_mov_b32_e32 v30, v2
	v_mov_b32_e32 v31, v2
	v_mov_b32_e32 v32, v2
	v_mov_b32_e32 v33, v2
	v_mov_b32_e32 v42, v2
	v_mov_b32_e32 v43, v2
	v_mov_b32_e32 v44, v2
	v_mov_b32_e32 v45, v2
	v_mov_b32_e32 v46, v2
	v_mov_b32_e32 v47, v2
	v_mov_b32_e32 v48, v2
	v_mov_b32_e32 v49, v2
	v_mov_b32_e32 v58, v2
	v_mov_b32_e32 v59, v2
	v_mov_b32_e32 v60, v2
	v_mov_b32_e32 v61, v2
	v_mov_b32_e32 v62, v2
	v_mov_b32_e32 v63, v2
	v_mov_b32_e32 v64, v2
	v_mov_b32_e32 v65, v2
	v_mov_b32_e32 v66, v2
	v_mov_b32_e32 v67, v2
	v_mov_b32_e32 v68, v2
	v_mov_b32_e32 v69, v2
	v_mov_b32_e32 v70, v2
	v_mov_b32_e32 v71, v2
	v_mov_b32_e32 v72, v2
	v_mov_b32_e32 v73, v2
	v_mov_b32_e32 v82, v2
	v_mov_b32_e32 v83, v2
	v_mov_b32_e32 v84, v2
	v_mov_b32_e32 v85, v2
	v_mov_b32_e32 v86, v2
	v_mov_b32_e32 v87, v2
	v_mov_b32_e32 v88, v2
	v_mov_b32_e32 v89, v2
	v_mov_b32_e32 v98, v2
	v_mov_b32_e32 v99, v2
	v_mov_b32_e32 v100, v2
	v_mov_b32_e32 v101, v2
	v_mov_b32_e32 v102, v2
	v_mov_b32_e32 v103, v2
	v_mov_b32_e32 v104, v2
	v_mov_b32_e32 v105, v2
	v_mov_b32_e32 v114, v2
	v_mov_b32_e32 v115, v2
	v_mov_b32_e32 v116, v2
	v_mov_b32_e32 v117, v2
	v_mov_b32_e32 v118, v2
	v_mov_b32_e32 v119, v2
	v_mov_b32_e32 v120, v2
	v_mov_b32_e32 v121, v2
	v_mov_b32_e32 v74, v2
	v_mov_b32_e32 v75, v2
	v_mov_b32_e32 v76, v2
	v_mov_b32_e32 v77, v2
	v_mov_b32_e32 v78, v2
	v_mov_b32_e32 v79, v2
	v_mov_b32_e32 v80, v2
	v_mov_b32_e32 v81, v2
	v_mov_b32_e32 v90, v2
	v_mov_b32_e32 v91, v2
	v_mov_b32_e32 v92, v2
	v_mov_b32_e32 v93, v2
	v_mov_b32_e32 v94, v2
	v_mov_b32_e32 v95, v2
	v_mov_b32_e32 v96, v2
	v_mov_b32_e32 v97, v2
	v_mov_b32_e32 v106, v2
	v_mov_b32_e32 v107, v2
	v_mov_b32_e32 v108, v2
	v_mov_b32_e32 v109, v2
	v_mov_b32_e32 v110, v2
	v_mov_b32_e32 v111, v2
	v_mov_b32_e32 v112, v2
	v_mov_b32_e32 v113, v2
	v_mov_b32_e32 v122, v2
	v_mov_b32_e32 v123, v2
	v_mov_b32_e32 v124, v2
	v_mov_b32_e32 v125, v2
	v_mov_b32_e32 v126, v2
	v_mov_b32_e32 v127, v2
	v_mov_b32_e32 v128, v2
	v_mov_b32_e32 v129, v2
	s_andn2_b64 vcc, exec, s[0:1]
	s_cbranch_vccnz .LBB0_818

; #define PG8_STAGE(bufoff, gbase, voff) do { _Pragma("unroll") for (int _i = 0; _i < 2; ++_i) \
;         __builtin_amdgcn_global_load_lds((const unsigned*)((const char*)(gbase) + (voff)[_i]), (PG8_LAS unsigned*)(lds + (bufoff) + ldsw + _i * 8192), 16, 0, 0); } while (0)
; #define PG8_LDA(dst, b, h) do { _Pragma("unroll") for (int m = 0; m < 4; ++m) _Pragma("unroll") for (int k = 0; k < 2; ++k) dst[m][k] = *(const PG8_LAS bf16x8*)(lds + PG8_SA(b, h) + aoff + m * 2048 + k * 1024); } while (0)
; #define PG8_LDB(dst, b, h) do { _Pragma("unroll") for (int n = 0; n < 2; ++n) _Pragma("unroll") for (int k = 0; k < 2; ++k) dst[n][k] = *(const PG8_LAS bf16x8*)(lds + PG8_SB(b, h) + boff + n * 2048 + k * 1024); } while (0)
; template <class Epi, class Sched, bool ALIGN_EPI = false, bool SP2 = false>
; __device__ __forceinline__ void gemm_phase(PG8_LAS unsigned char* lds, const Gemm g, const Sched& S, const Epi& E) {
;     ...
;         for (int t = 0; t < nt; t += 2) {
;             const bool last = (t == nt - 2);
;             const char* a1 = cA + (size_t)(t + 1) * kstep;
;             const char* a2 = last ? nA : cA + (size_t)(t + 2) * kstep; const char* b2 = last ? nB : cB + (size_t)(t + 2) * kstep;
;             const char* a3 = a2 + kstep; const char* b3 = b2 + kstep;
;             if (last && has_next) S.a_ready(nxt);
;             if constexpr (SP2) {
;             PG8_LDB(B0, 0, 0); PG8_LDB(B1, 0, 1); PG8_SCHED; PG8_LDA(At, 0, 0); PG8_STAGE(PG8_SA(1, 1), a1 + hstep, voffA);
;             PG8_WAIT_V(8); PG8_WAIT_L(0); PG8_BAR; PG8_MMA(0, 0, At, B0); PG8_MMA(0, 1, At, B1); PG8_BAR; PG8_SCHED;
;             PG8_LDA(At, 0, 1); PG8_STAGE(PG8_SB(0, 0), b2, voffB); PG8_STAGE(PG8_SB(0, 1), b2 + hstep, voffB); PG8_STAGE(PG8_SA(0, 0), a2, voffA);
;             PG8_WAIT_V(8); PG8_WAIT_L(0); PG8_BAR; PG8_MMA(1, 0, At, B0); PG8_MMA(1, 1, At, B1); PG8_BAR; PG8_SCHED;
;             PG8_LDB(B0, 1, 0); PG8_LDB(B1, 1, 1); PG8_SCHED; PG8_LDA(At, 1, 0); PG8_STAGE(PG8_SA(0, 1), a2 + hstep, voffA);
;             PG8_WAIT_V(8); PG8_WAIT_L(0); PG8_BAR; PG8_MMA(0, 0, At, B0); PG8_MMA(0, 1, At, B1); PG8_BAR; PG8_SCHED;
;             PG8_LDA(At, 1, 1); PG8_STAGE(PG8_SB(1, 0), b3, voffB); PG8_STAGE(PG8_SB(1, 1), b3 + hstep, voffB); PG8_STAGE(PG8_SA(1, 0), a3, voffA);
;             PG8_WAIT_V(8); PG8_WAIT_L(0); PG8_BAR; PG8_MMA(1, 0, At, B0); PG8_MMA(1, 1, At, B1); PG8_BAR; PG8_SCHED;
.LBB0_966:
	s_add_u32 s16, s14, 0xfff80080
	s_addc_u32 s17, s15, -1
	s_add_i32 s40, 0, 0x10000
	s_cmp_eq_u32 s37, 28
	s_cselect_b32 s19, s9, s17
	s_cselect_b32 s18, s33, s16
	s_cselect_b32 s17, s7, s36
	s_cselect_b32 s16, s34, s35
	s_add_i32 s42, 0, 0x14000
	v_add_u32_e32 v156, s40, v145
	v_add_u32_e32 v160, s42, v145
	ds_read_b128 v[140:143], v156
	ds_read_b128 v[148:151], v156 offset:1024
	ds_read_b128 v[152:155], v156 offset:2048
	ds_read_b128 v[156:159], v156 offset:3072
	ds_read_b128 v[164:167], v160
	ds_read_b128 v[172:175], v160 offset:1024
	ds_read_b128 v[176:179], v160 offset:2048
	ds_read_b128 v[180:183], v160 offset:3072
	s_add_i32 m0, s23, 0xc000
	ds_read_b128 v[200:203], v147
	ds_read_b128 v[204:207], v147 offset:1024
	ds_read_b128 v[208:211], v147 offset:2048
	ds_read_b128 v[212:215], v147 offset:3072
	ds_read_b128 v[216:219], v147 offset:4096
	ds_read_b128 v[220:223], v147 offset:5120
	ds_read_b128 v[224:227], v147 offset:6144
	ds_read_b128 v[228:231], v147 offset:7168
	global_load_lds_dwordx4 v136, s[14:15]
	s_add_i32 m0, s23, 0xe000
	s_nop 0
	global_load_lds_dwordx4 v138, s[14:15]
	s_waitcnt vmcnt(8)
	s_waitcnt lgkmcnt(0)
	s_barrier
	s_setprio 1
	s_waitcnt lgkmcnt(0)
	v_mfma_f32_16x16x32_bf16 v[126:129], v[140:143], v[200:203], v[126:129]
	v_mfma_f32_16x16x32_bf16 v[118:121], v[152:155], v[200:203], v[118:121]
	v_mfma_f32_16x16x32_bf16 v[110:113], v[140:143], v[208:211], v[110:113]
	v_mfma_f32_16x16x32_bf16 v[102:105], v[152:155], v[208:211], v[102:105]
	v_mfma_f32_16x16x32_bf16 v[94:97], v[140:143], v[216:219], v[94:97]
	v_mfma_f32_16x16x32_bf16 v[86:89], v[152:155], v[216:219], v[86:89]
	v_mfma_f32_16x16x32_bf16 v[78:81], v[140:143], v[224:227], v[78:81]
	v_mfma_f32_16x16x32_bf16 v[70:73], v[152:155], v[224:227], v[70:73]
	v_mfma_f32_16x16x32_bf16 v[126:129], v[148:151], v[204:207], v[126:129]
	v_mfma_f32_16x16x32_bf16 v[118:121], v[156:159], v[204:207], v[118:121]
	v_mfma_f32_16x16x32_bf16 v[110:113], v[148:151], v[212:215], v[110:113]
	v_mfma_f32_16x16x32_bf16 v[102:105], v[156:159], v[212:215], v[102:105]
	v_mfma_f32_16x16x32_bf16 v[94:97], v[148:151], v[220:223], v[94:97]
	v_mfma_f32_16x16x32_bf16 v[86:89], v[156:159], v[220:223], v[86:89]
	v_mfma_f32_16x16x32_bf16 v[78:81], v[148:151], v[228:231], v[78:81]
	v_mfma_f32_16x16x32_bf16 v[70:73], v[156:159], v[228:231], v[70:73]
	s_setprio 0
	s_setprio 1
	v_mfma_f32_16x16x32_bf16 v[122:125], v[164:167], v[200:203], v[122:125]
	v_mfma_f32_16x16x32_bf16 v[114:117], v[176:179], v[200:203], v[114:117]
	v_mfma_f32_16x16x32_bf16 v[106:109], v[164:167], v[208:211], v[106:109]
	v_mfma_f32_16x16x32_bf16 v[98:101], v[176:179], v[208:211], v[98:101]
	v_mfma_f32_16x16x32_bf16 v[90:93], v[164:167], v[216:219], v[90:93]
	v_mfma_f32_16x16x32_bf16 v[82:85], v[176:179], v[216:219], v[82:85]
	v_mfma_f32_16x16x32_bf16 v[74:77], v[164:167], v[224:227], v[74:77]
	v_mfma_f32_16x16x32_bf16 v[66:69], v[176:179], v[224:227], v[66:69]
	v_mfma_f32_16x16x32_bf16 v[122:125], v[172:175], v[204:207], v[122:125]
	v_mfma_f32_16x16x32_bf16 v[114:117], v[180:183], v[204:207], v[114:117]
	v_mfma_f32_16x16x32_bf16 v[106:109], v[172:175], v[212:215], v[106:109]
	v_mfma_f32_16x16x32_bf16 v[98:101], v[180:183], v[212:215], v[98:101]
	v_mfma_f32_16x16x32_bf16 v[90:93], v[172:175], v[220:223], v[90:93]
	v_mfma_f32_16x16x32_bf16 v[82:85], v[180:183], v[220:223], v[82:85]
	v_mfma_f32_16x16x32_bf16 v[74:77], v[172:175], v[228:231], v[74:77]
	v_mfma_f32_16x16x32_bf16 v[66:69], v[180:183], v[228:231], v[66:69]
	s_setprio 0
	s_barrier
	s_add_i32 s40, s40, s22
	s_add_u32 s48, s16, s44
	s_addc_u32 s49, s17, s45
	s_mov_b32 m0, s40
	ds_read_b128 v[200:203], v147 offset:16384
	ds_read_b128 v[204:207], v147 offset:17408
	ds_read_b128 v[208:211], v147 offset:18432
	ds_read_b128 v[212:215], v147 offset:19456
	ds_read_b128 v[216:219], v147 offset:20480
	ds_read_b128 v[220:223], v147 offset:21504
	ds_read_b128 v[224:227], v147 offset:22528
	ds_read_b128 v[228:231], v147 offset:23552
	global_load_lds_dwordx4 v0, s[16:17]
	s_add_i32 m0, s40, 0x2000
	s_add_u32 s40, s16, 0x80000
	s_addc_u32 s41, s17, 0
	s_add_i32 s42, s42, s22
	global_load_lds_dwordx4 v130, s[16:17]
	s_mov_b32 m0, s42
	s_nop 0
	global_load_lds_dwordx4 v0, s[40:41]
	s_add_i32 m0, s42, 0x2000
	s_nop 0
	global_load_lds_dwordx4 v130, s[40:41]
	s_add_u32 s50, s18, s44
	s_addc_u32 s51, s19, s45
	s_mov_b32 m0, s23
	s_nop 0
	global_load_lds_dwordx4 v134, s[18:19]
	s_mov_b32 m0, s24
	s_nop 0
	global_load_lds_dwordx4 v132, s[18:19]
	s_waitcnt vmcnt(8)
	s_waitcnt lgkmcnt(0)
	s_barrier
; #define PG8_STAGE(bufoff, gbase, voff) do { _Pragma("unroll") for (int _i = 0; _i < 2; ++_i) \
;         __builtin_amdgcn_global_load_lds((const unsigned*)((const char*)(gbase) + (voff)[_i]), (PG8_LAS unsigned*)(lds + (bufoff) + ldsw + _i * 8192), 16, 0, 0); } while (0)
; #define PG8_LDA(dst, b, h) do { _Pragma("unroll") for (int m = 0; m < 4; ++m) _Pragma("unroll") for (int k = 0; k < 2; ++k) dst[m][k] = *(const PG8_LAS bf16x8*)(lds + PG8_SA(b, h) + aoff + m * 2048 + k * 1024); } while (0)
; #define PG8_LDB(dst, b, h) do { _Pragma("unroll") for (int n = 0; n < 2; ++n) _Pragma("unroll") for (int k = 0; k < 2; ++k) dst[n][k] = *(const PG8_LAS bf16x8*)(lds + PG8_SB(b, h) + boff + n * 2048 + k * 1024); } while (0)
; #define PG8_MMA(ai, bj, At, Bt) do { __builtin_amdgcn_s_setprio(1); _Pragma("unroll") for (int m = 0; m < 4; ++m) _Pragma("unroll") for (int n = 0; n < 2; ++n) _Pragma("unroll") for (int k = 0; k < 2; ++k) \
;         acc[ai][bj][m][n] = __builtin_amdgcn_mfma_f32_16x16x32_bf16(Bt[n][k], At[m][k], acc[ai][bj][m][n], 0, 0, 0); __builtin_amdgcn_s_setprio(0); } while (0)
; #define PG8_WAIT_V(n) asm volatile("s_waitcnt vmcnt(" #n ")" ::: "memory")
; template <class Epi, class Sched, bool ALIGN_EPI = false, bool SP2 = false>
; __device__ __forceinline__ void gemm_phase(PG8_LAS unsigned char* lds, const Gemm g, const Sched& S, const Epi& E) {
;     ...
;             PG8_LDB(B0, 0, 0); PG8_LDB(B1, 0, 1); PG8_SCHED; PG8_LDA(At, 0, 0); PG8_STAGE(PG8_SA(1, 1), a1 + hstep, voffA);
;             PG8_WAIT_V(8); PG8_WAIT_L(0); PG8_BAR; PG8_MMA(0, 0, At, B0); PG8_MMA(0, 1, At, B1); PG8_BAR; PG8_SCHED;
;             PG8_LDA(At, 0, 1); PG8_STAGE(PG8_SB(0, 0), b2, voffB); PG8_STAGE(PG8_SB(0, 1), b2 + hstep, voffB); PG8_STAGE(PG8_SA(0, 0), a2, voffA);
;             PG8_WAIT_V(8); PG8_WAIT_L(0); PG8_BAR; PG8_MMA(1, 0, At, B0); PG8_MMA(1, 1, At, B1); PG8_BAR; PG8_SCHED;
;             PG8_LDB(B0, 1, 0); PG8_LDB(B1, 1, 1); PG8_SCHED; PG8_LDA(At, 1, 0); PG8_STAGE(PG8_SA(0, 1), a2 + hstep, voffA);
;             PG8_WAIT_V(8); PG8_WAIT_L(0); PG8_BAR; PG8_MMA(0, 0, At, B0); PG8_MMA(0, 1, At, B1); PG8_BAR; PG8_SCHED;
;             PG8_LDA(At, 1, 1); PG8_STAGE(PG8_SB(1, 0), b3, voffB); PG8_STAGE(PG8_SB(1, 1), b3 + hstep, voffB); PG8_STAGE(PG8_SA(1, 0), a3, voffA);
;             PG8_WAIT_V(8); PG8_WAIT_L(0); PG8_BAR; PG8_MMA(1, 0, At, B0); PG8_MMA(1, 1, At, B1); PG8_BAR; PG8_SCHED;
	s_setprio 1
	s_waitcnt lgkmcnt(0)
	v_mfma_f32_16x16x32_bf16 v[62:65], v[140:143], v[200:203], v[62:65]
	v_mfma_f32_16x16x32_bf16 v[54:57], v[152:155], v[200:203], v[54:57]
	v_mfma_f32_16x16x32_bf16 v[46:49], v[140:143], v[208:211], v[46:49]
	v_mfma_f32_16x16x32_bf16 v[38:41], v[152:155], v[208:211], v[38:41]
	v_mfma_f32_16x16x32_bf16 v[30:33], v[140:143], v[216:219], v[30:33]
	v_mfma_f32_16x16x32_bf16 v[22:25], v[152:155], v[216:219], v[22:25]
	v_mfma_f32_16x16x32_bf16 v[14:17], v[140:143], v[224:227], v[14:17]
	v_mfma_f32_16x16x32_bf16 v[6:9], v[152:155], v[224:227], v[6:9]
	v_mfma_f32_16x16x32_bf16 v[62:65], v[148:151], v[204:207], v[62:65]
	v_mfma_f32_16x16x32_bf16 v[54:57], v[156:159], v[204:207], v[54:57]
	v_mfma_f32_16x16x32_bf16 v[46:49], v[148:151], v[212:215], v[46:49]
	v_mfma_f32_16x16x32_bf16 v[38:41], v[156:159], v[212:215], v[38:41]
	v_mfma_f32_16x16x32_bf16 v[30:33], v[148:151], v[220:223], v[30:33]
	v_mfma_f32_16x16x32_bf16 v[22:25], v[156:159], v[220:223], v[22:25]
	v_mfma_f32_16x16x32_bf16 v[14:17], v[148:151], v[228:231], v[14:17]
	v_mfma_f32_16x16x32_bf16 v[6:9], v[156:159], v[228:231], v[6:9]
	s_setprio 0
	s_setprio 1
	v_mfma_f32_16x16x32_bf16 v[58:61], v[164:167], v[200:203], v[58:61]
	v_mfma_f32_16x16x32_bf16 v[50:53], v[176:179], v[200:203], v[50:53]
	v_mfma_f32_16x16x32_bf16 v[42:45], v[164:167], v[208:211], v[42:45]
	v_mfma_f32_16x16x32_bf16 v[34:37], v[176:179], v[208:211], v[34:37]
	v_mfma_f32_16x16x32_bf16 v[26:29], v[164:167], v[216:219], v[26:29]
	v_mfma_f32_16x16x32_bf16 v[18:21], v[176:179], v[216:219], v[18:21]
	v_mfma_f32_16x16x32_bf16 v[10:13], v[164:167], v[224:227], v[10:13]
	v_mfma_f32_16x16x32_bf16 v[2:5], v[176:179], v[224:227], v[2:5]
	v_mfma_f32_16x16x32_bf16 v[58:61], v[172:175], v[204:207], v[58:61]
	v_mfma_f32_16x16x32_bf16 v[50:53], v[180:183], v[204:207], v[50:53]
	v_mfma_f32_16x16x32_bf16 v[42:45], v[172:175], v[212:215], v[42:45]
	v_mfma_f32_16x16x32_bf16 v[34:37], v[180:183], v[212:215], v[34:37]
	v_mfma_f32_16x16x32_bf16 v[26:29], v[172:175], v[220:223], v[26:29]
	v_mfma_f32_16x16x32_bf16 v[18:21], v[180:183], v[220:223], v[18:21]
	v_mfma_f32_16x16x32_bf16 v[10:13], v[172:175], v[228:231], v[10:13]
	v_mfma_f32_16x16x32_bf16 v[2:5], v[180:183], v[228:231], v[2:5]
	s_setprio 0
	s_barrier
	s_add_i32 s40, 0, 0x18000
	s_add_i32 s41, 0, 0x1c000
	v_add_u32_e32 v156, s40, v145
	v_add_u32_e32 v162, s41, v145
	ds_read_b128 v[140:143], v156
	ds_read_b128 v[148:151], v156 offset:1024
	ds_read_b128 v[152:155], v156 offset:2048
	ds_read_b128 v[156:159], v156 offset:3072
	ds_read_b128 v[164:167], v162
	ds_read_b128 v[172:175], v162 offset:1024
	ds_read_b128 v[176:179], v162 offset:2048
	ds_read_b128 v[180:183], v162 offset:3072
	s_add_u32 s18, s18, 0x80000
	s_addc_u32 s19, s19, 0
	s_mov_b32 m0, s25
	ds_read_b128 v[200:203], v147 offset:32768
	ds_read_b128 v[204:207], v147 offset:33792
	ds_read_b128 v[208:211], v147 offset:34816
	ds_read_b128 v[212:215], v147 offset:35840
	ds_read_b128 v[216:219], v147 offset:36864
	ds_read_b128 v[220:223], v147 offset:37888
	ds_read_b128 v[224:227], v147 offset:38912
	ds_read_b128 v[228:231], v147 offset:39936
	global_load_lds_dwordx4 v134, s[18:19]
	s_mov_b32 m0, s26
	s_nop 0
	global_load_lds_dwordx4 v132, s[18:19]
	s_waitcnt vmcnt(8)
	s_waitcnt lgkmcnt(0)
	s_barrier
	s_setprio 1
	s_waitcnt lgkmcnt(0)
	v_mfma_f32_16x16x32_bf16 v[126:129], v[140:143], v[200:203], v[126:129]
	v_mfma_f32_16x16x32_bf16 v[118:121], v[152:155], v[200:203], v[118:121]
	v_mfma_f32_16x16x32_bf16 v[110:113], v[140:143], v[208:211], v[110:113]
	v_mfma_f32_16x16x32_bf16 v[102:105], v[152:155], v[208:211], v[102:105]
	v_mfma_f32_16x16x32_bf16 v[94:97], v[140:143], v[216:219], v[94:97]
	v_mfma_f32_16x16x32_bf16 v[86:89], v[152:155], v[216:219], v[86:89]
	v_mfma_f32_16x16x32_bf16 v[78:81], v[140:143], v[224:227], v[78:81]
	v_mfma_f32_16x16x32_bf16 v[70:73], v[152:155], v[224:227], v[70:73]
	v_mfma_f32_16x16x32_bf16 v[126:129], v[148:151], v[204:207], v[126:129]
	v_mfma_f32_16x16x32_bf16 v[118:121], v[156:159], v[204:207], v[118:121]
	v_mfma_f32_16x16x32_bf16 v[110:113], v[148:151], v[212:215], v[110:113]
	v_mfma_f32_16x16x32_bf16 v[102:105], v[156:159], v[212:215], v[102:105]
	v_mfma_f32_16x16x32_bf16 v[94:97], v[148:151], v[220:223], v[94:97]
	v_mfma_f32_16x16x32_bf16 v[86:89], v[156:159], v[220:223], v[86:89]
	v_mfma_f32_16x16x32_bf16 v[78:81], v[148:151], v[228:231], v[78:81]
	v_mfma_f32_16x16x32_bf16 v[70:73], v[156:159], v[228:231], v[70:73]
	s_setprio 0
	s_setprio 1
	v_mfma_f32_16x16x32_bf16 v[122:125], v[164:167], v[200:203], v[122:125]
	v_mfma_f32_16x16x32_bf16 v[114:117], v[176:179], v[200:203], v[114:117]
	v_mfma_f32_16x16x32_bf16 v[106:109], v[164:167], v[208:211], v[106:109]
	v_mfma_f32_16x16x32_bf16 v[98:101], v[176:179], v[208:211], v[98:101]
	v_mfma_f32_16x16x32_bf16 v[90:93], v[164:167], v[216:219], v[90:93]
	v_mfma_f32_16x16x32_bf16 v[82:85], v[176:179], v[216:219], v[82:85]
	v_mfma_f32_16x16x32_bf16 v[74:77], v[164:167], v[224:227], v[74:77]
	v_mfma_f32_16x16x32_bf16 v[66:69], v[176:179], v[224:227], v[66:69]
	v_mfma_f32_16x16x32_bf16 v[122:125], v[172:175], v[204:207], v[122:125]
	v_mfma_f32_16x16x32_bf16 v[114:117], v[180:183], v[204:207], v[114:117]
	v_mfma_f32_16x16x32_bf16 v[106:109], v[172:175], v[212:215], v[106:109]
	v_mfma_f32_16x16x32_bf16 v[98:101], v[180:183], v[212:215], v[98:101]
	v_mfma_f32_16x16x32_bf16 v[90:93], v[172:175], v[220:223], v[90:93]
	v_mfma_f32_16x16x32_bf16 v[82:85], v[180:183], v[220:223], v[82:85]
	v_mfma_f32_16x16x32_bf16 v[74:77], v[172:175], v[228:231], v[74:77]
	v_mfma_f32_16x16x32_bf16 v[66:69], v[180:183], v[228:231], v[66:69]
	s_setprio 0
	s_barrier
; #define PG8_STAGE(bufoff, gbase, voff) do { _Pragma("unroll") for (int _i = 0; _i < 2; ++_i) \
;         __builtin_amdgcn_global_load_lds((const unsigned*)((const char*)(gbase) + (voff)[_i]), (PG8_LAS unsigned*)(lds + (bufoff) + ldsw + _i * 8192), 16, 0, 0); } while (0)
; #define PG8_LDA(dst, b, h) do { _Pragma("unroll") for (int m = 0; m < 4; ++m) _Pragma("unroll") for (int k = 0; k < 2; ++k) dst[m][k] = *(const PG8_LAS bf16x8*)(lds + PG8_SA(b, h) + aoff + m * 2048 + k * 1024); } while (0)
; #define PG8_LDB(dst, b, h) do { _Pragma("unroll") for (int n = 0; n < 2; ++n) _Pragma("unroll") for (int k = 0; k < 2; ++k) dst[n][k] = *(const PG8_LAS bf16x8*)(lds + PG8_SB(b, h) + boff + n * 2048 + k * 1024); } while (0)
; #define PG8_MMA(ai, bj, At, Bt) do { __builtin_amdgcn_s_setprio(1); _Pragma("unroll") for (int m = 0; m < 4; ++m) _Pragma("unroll") for (int n = 0; n < 2; ++n) _Pragma("unroll") for (int k = 0; k < 2; ++k) \
;         acc[ai][bj][m][n] = __builtin_amdgcn_mfma_f32_16x16x32_bf16(Bt[n][k], At[m][k], acc[ai][bj][m][n], 0, 0, 0); __builtin_amdgcn_s_setprio(0); } while (0)
; template <class Epi, class Sched, bool ALIGN_EPI = false, bool SP2 = false>
; __device__ __forceinline__ void gemm_phase(PG8_LAS unsigned char* lds, const Gemm g, const Sched& S, const Epi& E) {
;     ...
;             PG8_LDB(B0, 0, 0); PG8_LDB(B1, 0, 1); PG8_SCHED; PG8_LDA(At, 0, 0); PG8_STAGE(PG8_SA(1, 1), a1 + hstep, voffA);
;             PG8_WAIT_V(8); PG8_WAIT_L(0); PG8_BAR; PG8_MMA(0, 0, At, B0); PG8_MMA(0, 1, At, B1); PG8_BAR; PG8_SCHED;
;             PG8_LDA(At, 0, 1); PG8_STAGE(PG8_SB(0, 0), b2, voffB); PG8_STAGE(PG8_SB(0, 1), b2 + hstep, voffB); PG8_STAGE(PG8_SA(0, 0), a2, voffA);
;             PG8_WAIT_V(8); PG8_WAIT_L(0); PG8_BAR; PG8_MMA(1, 0, At, B0); PG8_MMA(1, 1, At, B1); PG8_BAR; PG8_SCHED;
;             PG8_LDB(B0, 1, 0); PG8_LDB(B1, 1, 1); PG8_SCHED; PG8_LDA(At, 1, 0); PG8_STAGE(PG8_SA(0, 1), a2 + hstep, voffA);
;             PG8_WAIT_V(8); PG8_WAIT_L(0); PG8_BAR; PG8_MMA(0, 0, At, B0); PG8_MMA(0, 1, At, B1); PG8_BAR; PG8_SCHED;
;             PG8_LDA(At, 1, 1); PG8_STAGE(PG8_SB(1, 0), b3, voffB); PG8_STAGE(PG8_SB(1, 1), b3 + hstep, voffB); PG8_STAGE(PG8_SA(1, 0), a3, voffA);
;             PG8_WAIT_V(8); PG8_WAIT_L(0); PG8_BAR; PG8_MMA(1, 0, At, B0); PG8_MMA(1, 1, At, B1); PG8_BAR; PG8_SCHED;
;     ...
;         if constexpr (ALIGN_EPI) { if (wr == 0) PG8_BAR; }
	s_add_i32 s18, s40, s22
	s_mov_b32 m0, s18
	ds_read_b128 v[200:203], v147 offset:49152
	ds_read_b128 v[204:207], v147 offset:50176
	ds_read_b128 v[208:211], v147 offset:51200
	ds_read_b128 v[212:215], v147 offset:52224
	ds_read_b128 v[216:219], v147 offset:53248
	ds_read_b128 v[220:223], v147 offset:54272
	ds_read_b128 v[224:227], v147 offset:55296
	ds_read_b128 v[228:231], v147 offset:56320
	global_load_lds_dwordx4 v0, s[48:49]
	s_add_i32 m0, s18, 0x2000
	s_add_u32 s16, s16, 0x80080
	s_addc_u32 s17, s17, 0
	s_add_i32 s18, s41, s22
	global_load_lds_dwordx4 v130, s[48:49]
	s_mov_b32 m0, s18
	s_nop 0
	global_load_lds_dwordx4 v0, s[16:17]
	s_add_i32 m0, s18, 0x2000
	s_nop 0
	global_load_lds_dwordx4 v130, s[16:17]
	s_mov_b32 m0, s27
	s_nop 0
	global_load_lds_dwordx4 v134, s[50:51]
	s_mov_b32 m0, s28
	s_nop 0
	global_load_lds_dwordx4 v132, s[50:51]
	s_waitcnt vmcnt(8)
	s_waitcnt lgkmcnt(0)
	s_barrier
	s_setprio 1
	s_waitcnt lgkmcnt(0)
	v_mfma_f32_16x16x32_bf16 v[62:65], v[140:143], v[200:203], v[62:65]
	v_mfma_f32_16x16x32_bf16 v[54:57], v[152:155], v[200:203], v[54:57]
	v_mfma_f32_16x16x32_bf16 v[46:49], v[140:143], v[208:211], v[46:49]
	v_mfma_f32_16x16x32_bf16 v[38:41], v[152:155], v[208:211], v[38:41]
	v_mfma_f32_16x16x32_bf16 v[30:33], v[140:143], v[216:219], v[30:33]
	v_mfma_f32_16x16x32_bf16 v[22:25], v[152:155], v[216:219], v[22:25]
	v_mfma_f32_16x16x32_bf16 v[14:17], v[140:143], v[224:227], v[14:17]
	v_mfma_f32_16x16x32_bf16 v[6:9], v[152:155], v[224:227], v[6:9]
	v_mfma_f32_16x16x32_bf16 v[62:65], v[148:151], v[204:207], v[62:65]
	v_mfma_f32_16x16x32_bf16 v[54:57], v[156:159], v[204:207], v[54:57]
	v_mfma_f32_16x16x32_bf16 v[46:49], v[148:151], v[212:215], v[46:49]
	v_mfma_f32_16x16x32_bf16 v[38:41], v[156:159], v[212:215], v[38:41]
	v_mfma_f32_16x16x32_bf16 v[30:33], v[148:151], v[220:223], v[30:33]
	v_mfma_f32_16x16x32_bf16 v[22:25], v[156:159], v[220:223], v[22:25]
	v_mfma_f32_16x16x32_bf16 v[14:17], v[148:151], v[228:231], v[14:17]
	v_mfma_f32_16x16x32_bf16 v[6:9], v[156:159], v[228:231], v[6:9]
	s_setprio 0
	s_setprio 1
	v_mfma_f32_16x16x32_bf16 v[58:61], v[164:167], v[200:203], v[58:61]
	v_mfma_f32_16x16x32_bf16 v[50:53], v[176:179], v[200:203], v[50:53]
	v_mfma_f32_16x16x32_bf16 v[42:45], v[164:167], v[208:211], v[42:45]
	v_mfma_f32_16x16x32_bf16 v[34:37], v[176:179], v[208:211], v[34:37]
	v_mfma_f32_16x16x32_bf16 v[26:29], v[164:167], v[216:219], v[26:29]
	v_mfma_f32_16x16x32_bf16 v[18:21], v[176:179], v[216:219], v[18:21]
	v_mfma_f32_16x16x32_bf16 v[10:13], v[164:167], v[224:227], v[10:13]
	v_mfma_f32_16x16x32_bf16 v[2:5], v[176:179], v[224:227], v[2:5]
	v_mfma_f32_16x16x32_bf16 v[58:61], v[172:175], v[204:207], v[58:61]
	v_mfma_f32_16x16x32_bf16 v[50:53], v[180:183], v[204:207], v[50:53]
	v_mfma_f32_16x16x32_bf16 v[42:45], v[172:175], v[212:215], v[42:45]
	v_mfma_f32_16x16x32_bf16 v[34:37], v[180:183], v[212:215], v[34:37]
	v_mfma_f32_16x16x32_bf16 v[26:29], v[172:175], v[220:223], v[26:29]
	v_mfma_f32_16x16x32_bf16 v[18:21], v[180:183], v[220:223], v[18:21]
	v_mfma_f32_16x16x32_bf16 v[10:13], v[172:175], v[228:231], v[10:13]
	v_mfma_f32_16x16x32_bf16 v[2:5], v[180:183], v[228:231], v[2:5]
	s_setprio 0
	s_barrier
	s_add_i32 s37, s37, 2
	s_add_u32 s14, s14, 0x100
	s_addc_u32 s15, s15, 0
	s_add_u32 s35, s35, 0x100
	s_addc_u32 s36, s36, 0
	s_cmp_gt_u32 s37, 29
	s_cbranch_scc0 .LBB0_966
	s_and_b64 vcc, exec, s[4:5]
	s_cbranch_vccz .LBB0_969
	s_barrier

; #define PG8_STAGE(bufoff, gbase, voff) do { _Pragma("unroll") for (int _i = 0; _i < 2; ++_i) \
;         __builtin_amdgcn_global_load_lds((const unsigned*)((const char*)(gbase) + (voff)[_i]), (PG8_LAS unsigned*)(lds + (bufoff) + ldsw + _i * 8192), 16, 0, 0); } while (0)
; #define PG8_LDA(dst, b, h) do { _Pragma("unroll") for (int m = 0; m < 4; ++m) _Pragma("unroll") for (int k = 0; k < 2; ++k) dst[m][k] = *(const PG8_LAS bf16x8*)(lds + PG8_SA(b, h) + aoff + m * 2048 + k * 1024); } while (0)
; #define PG8_LDB(dst, b, h) do { _Pragma("unroll") for (int n = 0; n < 2; ++n) _Pragma("unroll") for (int k = 0; k < 2; ++k) dst[n][k] = *(const PG8_LAS bf16x8*)(lds + PG8_SB(b, h) + boff + n * 2048 + k * 1024); } while (0)
; template <class Epi, class Sched, bool ALIGN_EPI = false, bool SP2 = false>
; __device__ __forceinline__ void gemm_phase(PG8_LAS unsigned char* lds, const Gemm g, const Sched& S, const Epi& E) {
;     ...
;         for (int t = 0; t < nt; t += 2) {
;             const bool last = (t == nt - 2);
;             const char* a1 = cA + (size_t)(t + 1) * kstep;
;             const char* a2 = last ? nA : cA + (size_t)(t + 2) * kstep; const char* b2 = last ? nB : cB + (size_t)(t + 2) * kstep;
;             const char* a3 = a2 + kstep; const char* b3 = b2 + kstep;
;             if (last && has_next) S.a_ready(nxt);
;             if constexpr (SP2) {
;             PG8_LDB(B0, 0, 0); PG8_LDB(B1, 0, 1); PG8_SCHED; PG8_LDA(At, 0, 0); PG8_STAGE(PG8_SA(1, 1), a1 + hstep, voffA);
;             PG8_WAIT_V(8); PG8_WAIT_L(0); PG8_BAR; PG8_MMA(0, 0, At, B0); PG8_MMA(0, 1, At, B1); PG8_BAR; PG8_SCHED;
;             PG8_LDA(At, 0, 1); PG8_STAGE(PG8_SB(0, 0), b2, voffB); PG8_STAGE(PG8_SB(0, 1), b2 + hstep, voffB); PG8_STAGE(PG8_SA(0, 0), a2, voffA);
;             PG8_WAIT_V(8); PG8_WAIT_L(0); PG8_BAR; PG8_MMA(1, 0, At, B0); PG8_MMA(1, 1, At, B1); PG8_BAR; PG8_SCHED;
;             PG8_LDB(B0, 1, 0); PG8_LDB(B1, 1, 1); PG8_SCHED; PG8_LDA(At, 1, 0); PG8_STAGE(PG8_SA(0, 1), a2 + hstep, voffA);
;             PG8_WAIT_V(8); PG8_WAIT_L(0); PG8_BAR; PG8_MMA(0, 0, At, B0); PG8_MMA(0, 1, At, B1); PG8_BAR; PG8_SCHED;
;             PG8_LDA(At, 1, 1); PG8_STAGE(PG8_SB(1, 0), b3, voffB); PG8_STAGE(PG8_SB(1, 1), b3 + hstep, voffB); PG8_STAGE(PG8_SA(1, 0), a3, voffA);
;             PG8_WAIT_V(8); PG8_WAIT_L(0); PG8_BAR; PG8_MMA(1, 0, At, B0); PG8_MMA(1, 1, At, B1); PG8_BAR; PG8_SCHED;
.LBB0_1066:
	s_add_u32 s12, s6, s10
	s_addc_u32 s13, s7, s11
	s_add_u32 s12, s12, 0x100
	s_addc_u32 s13, s13, 0
	s_add_u32 s40, s37, s10
	s_addc_u32 s41, s38, s11
	s_add_i32 s42, 0, 0x10000
	s_cmpk_eq_i32 s10, 0x2b00
	s_cselect_b32 s15, s9, s13
	s_cselect_b32 s14, s8, s12
	v_add_u32_e32 v160, s42, v144
	s_cselect_b32 s13, s5, s41
	s_cselect_b32 s12, s4, s40
	s_add_i32 s43, 0, 0x14000
	ds_read_b128 v[146:149], v160
	ds_read_b128 v[150:153], v160 offset:1024
	ds_read_b128 v[156:159], v160 offset:2048
	ds_read_b128 v[164:167], v160 offset:3072
	v_add_u32_e32 v160, s43, v144
	ds_read_b128 v[172:175], v160
	ds_read_b128 v[180:183], v160 offset:1024
	ds_read_b128 v[200:203], v160 offset:2048
	ds_read_b128 v[204:207], v160 offset:3072
	v_lshl_add_u64 v[160:161], v[140:141], 0, s[10:11]
	s_add_i32 m0, s26, 0xc000
	ds_read_b128 v[208:211], v145
	ds_read_b128 v[212:215], v145 offset:1024
	ds_read_b128 v[216:219], v145 offset:2048
	ds_read_b128 v[220:223], v145 offset:3072
	ds_read_b128 v[224:227], v145 offset:4096
	ds_read_b128 v[228:231], v145 offset:5120
	ds_read_b128 v[232:235], v145 offset:6144
	ds_read_b128 v[236:239], v145 offset:7168
	global_load_lds_dwordx4 v[160:161], off
	v_lshl_add_u64 v[160:161], v[142:143], 0, s[10:11]
	s_add_i32 m0, s26, 0xe000
	s_nop 0
	global_load_lds_dwordx4 v[160:161], off
	s_waitcnt vmcnt(8)
	s_waitcnt lgkmcnt(0)
	s_barrier
	s_setprio 1
	s_waitcnt lgkmcnt(0)
	v_mfma_f32_16x16x32_bf16 v[126:129], v[146:149], v[208:211], v[126:129]
	v_mfma_f32_16x16x32_bf16 v[122:125], v[156:159], v[208:211], v[122:125]
	v_mfma_f32_16x16x32_bf16 v[110:113], v[146:149], v[216:219], v[110:113]
	v_mfma_f32_16x16x32_bf16 v[106:109], v[156:159], v[216:219], v[106:109]
	v_mfma_f32_16x16x32_bf16 v[94:97], v[146:149], v[224:227], v[94:97]
	v_mfma_f32_16x16x32_bf16 v[90:93], v[156:159], v[224:227], v[90:93]
	v_mfma_f32_16x16x32_bf16 v[78:81], v[146:149], v[232:235], v[78:81]
	v_mfma_f32_16x16x32_bf16 v[74:77], v[156:159], v[232:235], v[74:77]
	v_mfma_f32_16x16x32_bf16 v[126:129], v[150:153], v[212:215], v[126:129]
	v_mfma_f32_16x16x32_bf16 v[122:125], v[164:167], v[212:215], v[122:125]
	v_mfma_f32_16x16x32_bf16 v[110:113], v[150:153], v[220:223], v[110:113]
	v_mfma_f32_16x16x32_bf16 v[106:109], v[164:167], v[220:223], v[106:109]
	v_mfma_f32_16x16x32_bf16 v[94:97], v[150:153], v[228:231], v[94:97]
	v_mfma_f32_16x16x32_bf16 v[90:93], v[164:167], v[228:231], v[90:93]
	v_mfma_f32_16x16x32_bf16 v[78:81], v[150:153], v[236:239], v[78:81]
	v_mfma_f32_16x16x32_bf16 v[74:77], v[164:167], v[236:239], v[74:77]
	s_setprio 0
	s_setprio 1
	v_mfma_f32_16x16x32_bf16 v[118:121], v[172:175], v[208:211], v[118:121]
	v_mfma_f32_16x16x32_bf16 v[114:117], v[200:203], v[208:211], v[114:117]
	v_mfma_f32_16x16x32_bf16 v[102:105], v[172:175], v[216:219], v[102:105]
	v_mfma_f32_16x16x32_bf16 v[98:101], v[200:203], v[216:219], v[98:101]
	v_mfma_f32_16x16x32_bf16 v[86:89], v[172:175], v[224:227], v[86:89]
	v_mfma_f32_16x16x32_bf16 v[82:85], v[200:203], v[224:227], v[82:85]
	v_mfma_f32_16x16x32_bf16 v[70:73], v[172:175], v[232:235], v[70:73]
	v_mfma_f32_16x16x32_bf16 v[66:69], v[200:203], v[232:235], v[66:69]
	v_mfma_f32_16x16x32_bf16 v[118:121], v[180:183], v[212:215], v[118:121]
	v_mfma_f32_16x16x32_bf16 v[114:117], v[204:207], v[212:215], v[114:117]
	v_mfma_f32_16x16x32_bf16 v[102:105], v[180:183], v[220:223], v[102:105]
	v_mfma_f32_16x16x32_bf16 v[98:101], v[204:207], v[220:223], v[98:101]
	v_mfma_f32_16x16x32_bf16 v[86:89], v[180:183], v[228:231], v[86:89]
	v_mfma_f32_16x16x32_bf16 v[82:85], v[204:207], v[228:231], v[82:85]
	v_mfma_f32_16x16x32_bf16 v[70:73], v[180:183], v[236:239], v[70:73]
	v_mfma_f32_16x16x32_bf16 v[66:69], v[204:207], v[236:239], v[66:69]
	s_setprio 0
	s_barrier
	s_add_i32 s40, s42, s25
	s_add_u32 s84, s12, s44
	s_addc_u32 s85, s13, s45
	s_mov_b32 m0, s40
	ds_read_b128 v[208:211], v145 offset:16384
	ds_read_b128 v[212:215], v145 offset:17408
	ds_read_b128 v[216:219], v145 offset:18432
	ds_read_b128 v[220:223], v145 offset:19456
	ds_read_b128 v[224:227], v145 offset:20480
	ds_read_b128 v[228:231], v145 offset:21504
	ds_read_b128 v[232:235], v145 offset:22528
	ds_read_b128 v[236:239], v145 offset:23552
	global_load_lds_dwordx4 v0, s[12:13]
	s_add_i32 m0, s40, 0x2000
	s_add_u32 s40, s12, 0x160000
	s_addc_u32 s41, s13, 0
	s_add_i32 s42, s43, s25
	global_load_lds_dwordx4 v130, s[12:13]
	s_mov_b32 m0, s42
	s_nop 0
	global_load_lds_dwordx4 v0, s[40:41]
	s_add_i32 m0, s42, 0x2000
	s_nop 0
	global_load_lds_dwordx4 v130, s[40:41]
	s_add_u32 s86, s14, s44
	s_addc_u32 s87, s15, s45
	s_mov_b32 m0, s26
	s_nop 0
	global_load_lds_dwordx4 v134, s[14:15]
	s_mov_b32 m0, s27
	s_nop 0
	global_load_lds_dwordx4 v132, s[14:15]
	s_waitcnt vmcnt(8)
	s_waitcnt lgkmcnt(0)
	s_barrier
; #define PG8_STAGE(bufoff, gbase, voff) do { _Pragma("unroll") for (int _i = 0; _i < 2; ++_i) \
;         __builtin_amdgcn_global_load_lds((const unsigned*)((const char*)(gbase) + (voff)[_i]), (PG8_LAS unsigned*)(lds + (bufoff) + ldsw + _i * 8192), 16, 0, 0); } while (0)
; #define PG8_LDA(dst, b, h) do { _Pragma("unroll") for (int m = 0; m < 4; ++m) _Pragma("unroll") for (int k = 0; k < 2; ++k) dst[m][k] = *(const PG8_LAS bf16x8*)(lds + PG8_SA(b, h) + aoff + m * 2048 + k * 1024); } while (0)
; #define PG8_LDB(dst, b, h) do { _Pragma("unroll") for (int n = 0; n < 2; ++n) _Pragma("unroll") for (int k = 0; k < 2; ++k) dst[n][k] = *(const PG8_LAS bf16x8*)(lds + PG8_SB(b, h) + boff + n * 2048 + k * 1024); } while (0)
; #define PG8_MMA(ai, bj, At, Bt) do { __builtin_amdgcn_s_setprio(1); _Pragma("unroll") for (int m = 0; m < 4; ++m) _Pragma("unroll") for (int n = 0; n < 2; ++n) _Pragma("unroll") for (int k = 0; k < 2; ++k) \
;         acc[ai][bj][m][n] = __builtin_amdgcn_mfma_f32_16x16x32_bf16(Bt[n][k], At[m][k], acc[ai][bj][m][n], 0, 0, 0); __builtin_amdgcn_s_setprio(0); } while (0)
; #define PG8_WAIT_V(n) asm volatile("s_waitcnt vmcnt(" #n ")" ::: "memory")
; template <class Epi, class Sched, bool ALIGN_EPI = false, bool SP2 = false>
; __device__ __forceinline__ void gemm_phase(PG8_LAS unsigned char* lds, const Gemm g, const Sched& S, const Epi& E) {
;     ...
;             PG8_LDB(B0, 0, 0); PG8_LDB(B1, 0, 1); PG8_SCHED; PG8_LDA(At, 0, 0); PG8_STAGE(PG8_SA(1, 1), a1 + hstep, voffA);
;             PG8_WAIT_V(8); PG8_WAIT_L(0); PG8_BAR; PG8_MMA(0, 0, At, B0); PG8_MMA(0, 1, At, B1); PG8_BAR; PG8_SCHED;
;             PG8_LDA(At, 0, 1); PG8_STAGE(PG8_SB(0, 0), b2, voffB); PG8_STAGE(PG8_SB(0, 1), b2 + hstep, voffB); PG8_STAGE(PG8_SA(0, 0), a2, voffA);
;             PG8_WAIT_V(8); PG8_WAIT_L(0); PG8_BAR; PG8_MMA(1, 0, At, B0); PG8_MMA(1, 1, At, B1); PG8_BAR; PG8_SCHED;
;             PG8_LDB(B0, 1, 0); PG8_LDB(B1, 1, 1); PG8_SCHED; PG8_LDA(At, 1, 0); PG8_STAGE(PG8_SA(0, 1), a2 + hstep, voffA);
;             PG8_WAIT_V(8); PG8_WAIT_L(0); PG8_BAR; PG8_MMA(0, 0, At, B0); PG8_MMA(0, 1, At, B1); PG8_BAR; PG8_SCHED;
;             PG8_LDA(At, 1, 1); PG8_STAGE(PG8_SB(1, 0), b3, voffB); PG8_STAGE(PG8_SB(1, 1), b3 + hstep, voffB); PG8_STAGE(PG8_SA(1, 0), a3, voffA);
;             PG8_WAIT_V(8); PG8_WAIT_L(0); PG8_BAR; PG8_MMA(1, 0, At, B0); PG8_MMA(1, 1, At, B1); PG8_BAR; PG8_SCHED;
	s_setprio 1
	s_waitcnt lgkmcnt(0)
	v_mfma_f32_16x16x32_bf16 v[62:65], v[146:149], v[208:211], v[62:65]
	v_mfma_f32_16x16x32_bf16 v[58:61], v[156:159], v[208:211], v[58:61]
	v_mfma_f32_16x16x32_bf16 v[46:49], v[146:149], v[216:219], v[46:49]
	v_mfma_f32_16x16x32_bf16 v[42:45], v[156:159], v[216:219], v[42:45]
	v_mfma_f32_16x16x32_bf16 v[30:33], v[146:149], v[224:227], v[30:33]
	v_mfma_f32_16x16x32_bf16 v[26:29], v[156:159], v[224:227], v[26:29]
	v_mfma_f32_16x16x32_bf16 v[14:17], v[146:149], v[232:235], v[14:17]
	v_mfma_f32_16x16x32_bf16 v[10:13], v[156:159], v[232:235], v[10:13]
	v_mfma_f32_16x16x32_bf16 v[62:65], v[150:153], v[212:215], v[62:65]
	v_mfma_f32_16x16x32_bf16 v[58:61], v[164:167], v[212:215], v[58:61]
	v_mfma_f32_16x16x32_bf16 v[46:49], v[150:153], v[220:223], v[46:49]
	v_mfma_f32_16x16x32_bf16 v[42:45], v[164:167], v[220:223], v[42:45]
	v_mfma_f32_16x16x32_bf16 v[30:33], v[150:153], v[228:231], v[30:33]
	v_mfma_f32_16x16x32_bf16 v[26:29], v[164:167], v[228:231], v[26:29]
	v_mfma_f32_16x16x32_bf16 v[14:17], v[150:153], v[236:239], v[14:17]
	v_mfma_f32_16x16x32_bf16 v[10:13], v[164:167], v[236:239], v[10:13]
	s_setprio 0
	s_setprio 1
	v_mfma_f32_16x16x32_bf16 v[54:57], v[172:175], v[208:211], v[54:57]
	v_mfma_f32_16x16x32_bf16 v[50:53], v[200:203], v[208:211], v[50:53]
	v_mfma_f32_16x16x32_bf16 v[38:41], v[172:175], v[216:219], v[38:41]
	v_mfma_f32_16x16x32_bf16 v[34:37], v[200:203], v[216:219], v[34:37]
	v_mfma_f32_16x16x32_bf16 v[22:25], v[172:175], v[224:227], v[22:25]
	v_mfma_f32_16x16x32_bf16 v[18:21], v[200:203], v[224:227], v[18:21]
	v_mfma_f32_16x16x32_bf16 v[6:9], v[172:175], v[232:235], v[6:9]
	v_mfma_f32_16x16x32_bf16 v[2:5], v[200:203], v[232:235], v[2:5]
	v_mfma_f32_16x16x32_bf16 v[54:57], v[180:183], v[212:215], v[54:57]
	v_mfma_f32_16x16x32_bf16 v[50:53], v[204:207], v[212:215], v[50:53]
	v_mfma_f32_16x16x32_bf16 v[38:41], v[180:183], v[220:223], v[38:41]
	v_mfma_f32_16x16x32_bf16 v[34:37], v[204:207], v[220:223], v[34:37]
	v_mfma_f32_16x16x32_bf16 v[22:25], v[180:183], v[228:231], v[22:25]
	v_mfma_f32_16x16x32_bf16 v[18:21], v[204:207], v[228:231], v[18:21]
	v_mfma_f32_16x16x32_bf16 v[6:9], v[180:183], v[236:239], v[6:9]
	v_mfma_f32_16x16x32_bf16 v[2:5], v[204:207], v[236:239], v[2:5]
	s_setprio 0
	s_barrier
	s_add_i32 s40, 0, 0x18000
	v_add_u32_e32 v162, s40, v144
	s_add_i32 s41, 0, 0x1c000
	ds_read_b128 v[146:149], v162
	ds_read_b128 v[150:153], v162 offset:1024
	ds_read_b128 v[156:159], v162 offset:2048
	ds_read_b128 v[164:167], v162 offset:3072
	v_add_u32_e32 v162, s41, v144
	ds_read_b128 v[172:175], v162
	ds_read_b128 v[180:183], v162 offset:1024
	ds_read_b128 v[200:203], v162 offset:2048
	ds_read_b128 v[204:207], v162 offset:3072
	s_add_u32 s14, s14, 0x160000
	s_addc_u32 s15, s15, 0
	s_mov_b32 m0, s28
	ds_read_b128 v[208:211], v145 offset:32768
	ds_read_b128 v[212:215], v145 offset:33792
	ds_read_b128 v[216:219], v145 offset:34816
	ds_read_b128 v[220:223], v145 offset:35840
	ds_read_b128 v[224:227], v145 offset:36864
	ds_read_b128 v[228:231], v145 offset:37888
	ds_read_b128 v[232:235], v145 offset:38912
	ds_read_b128 v[236:239], v145 offset:39936
	global_load_lds_dwordx4 v134, s[14:15]
	s_mov_b32 m0, s29
	s_nop 0
	global_load_lds_dwordx4 v132, s[14:15]
	s_waitcnt vmcnt(8)
	s_waitcnt lgkmcnt(0)
	s_barrier
	s_setprio 1
	s_waitcnt lgkmcnt(0)
	v_mfma_f32_16x16x32_bf16 v[126:129], v[146:149], v[208:211], v[126:129]
	v_mfma_f32_16x16x32_bf16 v[122:125], v[156:159], v[208:211], v[122:125]
	v_mfma_f32_16x16x32_bf16 v[110:113], v[146:149], v[216:219], v[110:113]
	v_mfma_f32_16x16x32_bf16 v[106:109], v[156:159], v[216:219], v[106:109]
	v_mfma_f32_16x16x32_bf16 v[94:97], v[146:149], v[224:227], v[94:97]
	v_mfma_f32_16x16x32_bf16 v[90:93], v[156:159], v[224:227], v[90:93]
	v_mfma_f32_16x16x32_bf16 v[78:81], v[146:149], v[232:235], v[78:81]
	v_mfma_f32_16x16x32_bf16 v[74:77], v[156:159], v[232:235], v[74:77]
	v_mfma_f32_16x16x32_bf16 v[126:129], v[150:153], v[212:215], v[126:129]
	v_mfma_f32_16x16x32_bf16 v[122:125], v[164:167], v[212:215], v[122:125]
	v_mfma_f32_16x16x32_bf16 v[110:113], v[150:153], v[220:223], v[110:113]
	v_mfma_f32_16x16x32_bf16 v[106:109], v[164:167], v[220:223], v[106:109]
	v_mfma_f32_16x16x32_bf16 v[94:97], v[150:153], v[228:231], v[94:97]
	v_mfma_f32_16x16x32_bf16 v[90:93], v[164:167], v[228:231], v[90:93]
	v_mfma_f32_16x16x32_bf16 v[78:81], v[150:153], v[236:239], v[78:81]
	v_mfma_f32_16x16x32_bf16 v[74:77], v[164:167], v[236:239], v[74:77]
	s_setprio 0
	s_setprio 1
	v_mfma_f32_16x16x32_bf16 v[118:121], v[172:175], v[208:211], v[118:121]
	v_mfma_f32_16x16x32_bf16 v[114:117], v[200:203], v[208:211], v[114:117]
	v_mfma_f32_16x16x32_bf16 v[102:105], v[172:175], v[216:219], v[102:105]
	v_mfma_f32_16x16x32_bf16 v[98:101], v[200:203], v[216:219], v[98:101]
	v_mfma_f32_16x16x32_bf16 v[86:89], v[172:175], v[224:227], v[86:89]
	v_mfma_f32_16x16x32_bf16 v[82:85], v[200:203], v[224:227], v[82:85]
	v_mfma_f32_16x16x32_bf16 v[70:73], v[172:175], v[232:235], v[70:73]
	v_mfma_f32_16x16x32_bf16 v[66:69], v[200:203], v[232:235], v[66:69]
	v_mfma_f32_16x16x32_bf16 v[118:121], v[180:183], v[212:215], v[118:121]
	v_mfma_f32_16x16x32_bf16 v[114:117], v[204:207], v[212:215], v[114:117]
	v_mfma_f32_16x16x32_bf16 v[102:105], v[180:183], v[220:223], v[102:105]
	v_mfma_f32_16x16x32_bf16 v[98:101], v[204:207], v[220:223], v[98:101]
	v_mfma_f32_16x16x32_bf16 v[86:89], v[180:183], v[228:231], v[86:89]
	v_mfma_f32_16x16x32_bf16 v[82:85], v[204:207], v[228:231], v[82:85]
	v_mfma_f32_16x16x32_bf16 v[70:73], v[180:183], v[236:239], v[70:73]
	v_mfma_f32_16x16x32_bf16 v[66:69], v[204:207], v[236:239], v[66:69]
	s_setprio 0
	s_barrier
; #define PG8_STAGE(bufoff, gbase, voff) do { _Pragma("unroll") for (int _i = 0; _i < 2; ++_i) \
;         __builtin_amdgcn_global_load_lds((const unsigned*)((const char*)(gbase) + (voff)[_i]), (PG8_LAS unsigned*)(lds + (bufoff) + ldsw + _i * 8192), 16, 0, 0); } while (0)
; #define PG8_LDA(dst, b, h) do { _Pragma("unroll") for (int m = 0; m < 4; ++m) _Pragma("unroll") for (int k = 0; k < 2; ++k) dst[m][k] = *(const PG8_LAS bf16x8*)(lds + PG8_SA(b, h) + aoff + m * 2048 + k * 1024); } while (0)
; #define PG8_LDB(dst, b, h) do { _Pragma("unroll") for (int n = 0; n < 2; ++n) _Pragma("unroll") for (int k = 0; k < 2; ++k) dst[n][k] = *(const PG8_LAS bf16x8*)(lds + PG8_SB(b, h) + boff + n * 2048 + k * 1024); } while (0)
; #define PG8_WAIT_V(n) asm volatile("s_waitcnt vmcnt(" #n ")" ::: "memory")
; template <class Epi, class Sched, bool ALIGN_EPI = false, bool SP2 = false>
; __device__ __forceinline__ void gemm_phase(PG8_LAS unsigned char* lds, const Gemm g, const Sched& S, const Epi& E) {
;     ...
;             PG8_LDB(B0, 0, 0); PG8_LDB(B1, 0, 1); PG8_SCHED; PG8_LDA(At, 0, 0); PG8_STAGE(PG8_SA(1, 1), a1 + hstep, voffA);
;             PG8_WAIT_V(8); PG8_WAIT_L(0); PG8_BAR; PG8_MMA(0, 0, At, B0); PG8_MMA(0, 1, At, B1); PG8_BAR; PG8_SCHED;
;             PG8_LDA(At, 0, 1); PG8_STAGE(PG8_SB(0, 0), b2, voffB); PG8_STAGE(PG8_SB(0, 1), b2 + hstep, voffB); PG8_STAGE(PG8_SA(0, 0), a2, voffA);
;             PG8_WAIT_V(8); PG8_WAIT_L(0); PG8_BAR; PG8_MMA(1, 0, At, B0); PG8_MMA(1, 1, At, B1); PG8_BAR; PG8_SCHED;
;             PG8_LDB(B0, 1, 0); PG8_LDB(B1, 1, 1); PG8_SCHED; PG8_LDA(At, 1, 0); PG8_STAGE(PG8_SA(0, 1), a2 + hstep, voffA);
;             PG8_WAIT_V(8); PG8_WAIT_L(0); PG8_BAR; PG8_MMA(0, 0, At, B0); PG8_MMA(0, 1, At, B1); PG8_BAR; PG8_SCHED;
;             PG8_LDA(At, 1, 1); PG8_STAGE(PG8_SB(1, 0), b3, voffB); PG8_STAGE(PG8_SB(1, 1), b3 + hstep, voffB); PG8_STAGE(PG8_SA(1, 0), a3, voffA);
;             PG8_WAIT_V(8); PG8_WAIT_L(0); PG8_BAR; PG8_MMA(1, 0, At, B0); PG8_MMA(1, 1, At, B1); PG8_BAR; PG8_SCHED;
;     ...
;         if (!has_next) break;
; #pragma unroll
;         for (int a = 0; a < 2; ++a)
; #pragma unroll
;             for (int b = 0; b < 2; ++b)
; #pragma unroll
;                 for (int m = 0; m < 4; ++m)
; #pragma unroll
;                     for (int n = 0; n < 2; ++n) acc[a][b][m][n] = (f32x4){0.f, 0.f, 0.f, 0.f};
;         cur = nxt; cA = nA; cB = nB; ++ui;
	s_add_i32 s14, s40, s25
	s_mov_b32 m0, s14
	ds_read_b128 v[208:211], v145 offset:49152
	ds_read_b128 v[212:215], v145 offset:50176
	ds_read_b128 v[216:219], v145 offset:51200
	ds_read_b128 v[220:223], v145 offset:52224
	ds_read_b128 v[224:227], v145 offset:53248
	ds_read_b128 v[228:231], v145 offset:54272
	ds_read_b128 v[232:235], v145 offset:55296
	ds_read_b128 v[236:239], v145 offset:56320
	global_load_lds_dwordx4 v0, s[84:85]
	s_add_i32 m0, s14, 0x2000
	s_add_u32 s12, s12, 0x160080
	s_addc_u32 s13, s13, 0
	s_add_i32 s14, s41, s25
	global_load_lds_dwordx4 v130, s[84:85]
	s_mov_b32 m0, s14
	s_nop 0
	global_load_lds_dwordx4 v0, s[12:13]
	s_add_i32 m0, s14, 0x2000
	s_nop 0
	global_load_lds_dwordx4 v130, s[12:13]
	s_mov_b32 m0, s30
	s_nop 0
	global_load_lds_dwordx4 v134, s[86:87]
	s_mov_b32 m0, s31
	s_nop 0
	global_load_lds_dwordx4 v132, s[86:87]
	s_waitcnt vmcnt(8)
	s_waitcnt lgkmcnt(0)
	s_barrier
	s_setprio 1
	s_waitcnt lgkmcnt(0)
	v_mfma_f32_16x16x32_bf16 v[62:65], v[146:149], v[208:211], v[62:65]
	v_mfma_f32_16x16x32_bf16 v[58:61], v[156:159], v[208:211], v[58:61]
	v_mfma_f32_16x16x32_bf16 v[46:49], v[146:149], v[216:219], v[46:49]
	v_mfma_f32_16x16x32_bf16 v[42:45], v[156:159], v[216:219], v[42:45]
	v_mfma_f32_16x16x32_bf16 v[30:33], v[146:149], v[224:227], v[30:33]
	v_mfma_f32_16x16x32_bf16 v[26:29], v[156:159], v[224:227], v[26:29]
	v_mfma_f32_16x16x32_bf16 v[14:17], v[146:149], v[232:235], v[14:17]
	v_mfma_f32_16x16x32_bf16 v[10:13], v[156:159], v[232:235], v[10:13]
	v_mfma_f32_16x16x32_bf16 v[62:65], v[150:153], v[212:215], v[62:65]
	v_mfma_f32_16x16x32_bf16 v[58:61], v[164:167], v[212:215], v[58:61]
	v_mfma_f32_16x16x32_bf16 v[46:49], v[150:153], v[220:223], v[46:49]
	v_mfma_f32_16x16x32_bf16 v[42:45], v[164:167], v[220:223], v[42:45]
	v_mfma_f32_16x16x32_bf16 v[30:33], v[150:153], v[228:231], v[30:33]
	v_mfma_f32_16x16x32_bf16 v[26:29], v[164:167], v[228:231], v[26:29]
	v_mfma_f32_16x16x32_bf16 v[14:17], v[150:153], v[236:239], v[14:17]
	v_mfma_f32_16x16x32_bf16 v[10:13], v[164:167], v[236:239], v[10:13]
	s_setprio 0
	s_setprio 1
	v_mfma_f32_16x16x32_bf16 v[54:57], v[172:175], v[208:211], v[54:57]
	v_mfma_f32_16x16x32_bf16 v[50:53], v[200:203], v[208:211], v[50:53]
	v_mfma_f32_16x16x32_bf16 v[38:41], v[172:175], v[216:219], v[38:41]
	v_mfma_f32_16x16x32_bf16 v[34:37], v[200:203], v[216:219], v[34:37]
	v_mfma_f32_16x16x32_bf16 v[22:25], v[172:175], v[224:227], v[22:25]
	v_mfma_f32_16x16x32_bf16 v[18:21], v[200:203], v[224:227], v[18:21]
	v_mfma_f32_16x16x32_bf16 v[6:9], v[172:175], v[232:235], v[6:9]
	v_mfma_f32_16x16x32_bf16 v[2:5], v[200:203], v[232:235], v[2:5]
	v_mfma_f32_16x16x32_bf16 v[54:57], v[180:183], v[212:215], v[54:57]
	v_mfma_f32_16x16x32_bf16 v[50:53], v[204:207], v[212:215], v[50:53]
	v_mfma_f32_16x16x32_bf16 v[38:41], v[180:183], v[220:223], v[38:41]
	v_mfma_f32_16x16x32_bf16 v[34:37], v[204:207], v[220:223], v[34:37]
	v_mfma_f32_16x16x32_bf16 v[22:25], v[180:183], v[228:231], v[22:25]
	v_mfma_f32_16x16x32_bf16 v[18:21], v[204:207], v[228:231], v[18:21]
	v_mfma_f32_16x16x32_bf16 v[6:9], v[180:183], v[236:239], v[6:9]
	v_mfma_f32_16x16x32_bf16 v[2:5], v[204:207], v[236:239], v[2:5]
	s_setprio 0
	s_barrier
	s_add_i32 s39, s39, 2
	s_add_u32 s10, s10, 0x100
	s_addc_u32 s11, s11, 0
	s_cmpk_gt_u32 s39, 0x55
	s_cbranch_scc0 .LBB0_1066
	s_add_u32 s10, s37, 0xffffff00
	s_addc_u32 s11, s38, -1
	s_and_b64 vcc, exec, s[2:3]
	s_cbranch_vccnz .LBB0_1053
	v_mov_b32_e32 v2, 0
	s_mov_b32 s21, s34
	s_mov_b32 s20, s35
	s_mov_b64 s[6:7], s[8:9]
	s_mov_b32 s33, s36
	v_mov_b32_e32 v3, v2
	v_mov_b32_e32 v4, v2
	v_mov_b32_e32 v5, v2
	v_mov_b32_e32 v6, v2
	v_mov_b32_e32 v7, v2
	v_mov_b32_e32 v8, v2
	v_mov_b32_e32 v9, v2
	v_mov_b32_e32 v18, v2
	v_mov_b32_e32 v19, v2
	v_mov_b32_e32 v20, v2
	v_mov_b32_e32 v21, v2
	v_mov_b32_e32 v22, v2
	v_mov_b32_e32 v23, v2
	v_mov_b32_e32 v24, v2
	v_mov_b32_e32 v25, v2
	v_mov_b32_e32 v34, v2
	v_mov_b32_e32 v35, v2
	v_mov_b32_e32 v36, v2
	v_mov_b32_e32 v37, v2
	v_mov_b32_e32 v38, v2
	v_mov_b32_e32 v39, v2
	v_mov_b32_e32 v40, v2
	v_mov_b32_e32 v41, v2
	v_mov_b32_e32 v50, v2
	v_mov_b32_e32 v51, v2
	v_mov_b32_e32 v52, v2
	v_mov_b32_e32 v53, v2
	v_mov_b32_e32 v54, v2
	v_mov_b32_e32 v55, v2
	v_mov_b32_e32 v56, v2
	v_mov_b32_e32 v57, v2
	v_mov_b32_e32 v10, v2
	v_mov_b32_e32 v11, v2
	v_mov_b32_e32 v12, v2
	v_mov_b32_e32 v13, v2
	v_mov_b32_e32 v14, v2
	v_mov_b32_e32 v15, v2
	v_mov_b32_e32 v16, v2
	v_mov_b32_e32 v17, v2
	v_mov_b32_e32 v26, v2
	v_mov_b32_e32 v27, v2
	v_mov_b32_e32 v28, v2
	v_mov_b32_e32 v29, v2
	v_mov_b32_e32 v30, v2
	v_mov_b32_e32 v31, v2
	v_mov_b32_e32 v32, v2
	v_mov_b32_e32 v33, v2
	v_mov_b32_e32 v42, v2
	v_mov_b32_e32 v43, v2
	v_mov_b32_e32 v44, v2
	v_mov_b32_e32 v45, v2
	v_mov_b32_e32 v46, v2
	v_mov_b32_e32 v47, v2
	v_mov_b32_e32 v48, v2
	v_mov_b32_e32 v49, v2
	v_mov_b32_e32 v58, v2
	v_mov_b32_e32 v59, v2
	v_mov_b32_e32 v60, v2
	v_mov_b32_e32 v61, v2
	v_mov_b32_e32 v62, v2
	v_mov_b32_e32 v63, v2
	v_mov_b32_e32 v64, v2
	v_mov_b32_e32 v65, v2
	v_mov_b32_e32 v66, v2
	v_mov_b32_e32 v67, v2
	v_mov_b32_e32 v68, v2
	v_mov_b32_e32 v69, v2
	v_mov_b32_e32 v70, v2
	v_mov_b32_e32 v71, v2
	v_mov_b32_e32 v72, v2
	v_mov_b32_e32 v73, v2
	v_mov_b32_e32 v82, v2
	v_mov_b32_e32 v83, v2
	v_mov_b32_e32 v84, v2
	v_mov_b32_e32 v85, v2
	v_mov_b32_e32 v86, v2
	v_mov_b32_e32 v87, v2
	v_mov_b32_e32 v88, v2
	v_mov_b32_e32 v89, v2
	v_mov_b32_e32 v98, v2
	v_mov_b32_e32 v99, v2
	v_mov_b32_e32 v100, v2
	v_mov_b32_e32 v101, v2
	v_mov_b32_e32 v102, v2
	v_mov_b32_e32 v103, v2
	v_mov_b32_e32 v104, v2
	v_mov_b32_e32 v105, v2
	v_mov_b32_e32 v114, v2
	v_mov_b32_e32 v115, v2
	v_mov_b32_e32 v116, v2
	v_mov_b32_e32 v117, v2
	v_mov_b32_e32 v118, v2
	v_mov_b32_e32 v119, v2
	v_mov_b32_e32 v120, v2
	v_mov_b32_e32 v121, v2
	v_mov_b32_e32 v74, v2
	v_mov_b32_e32 v75, v2
	v_mov_b32_e32 v76, v2
	v_mov_b32_e32 v77, v2
	v_mov_b32_e32 v78, v2
	v_mov_b32_e32 v79, v2
	v_mov_b32_e32 v80, v2
	v_mov_b32_e32 v81, v2
	v_mov_b32_e32 v90, v2
	v_mov_b32_e32 v91, v2
	v_mov_b32_e32 v92, v2
	v_mov_b32_e32 v93, v2
	v_mov_b32_e32 v94, v2
	v_mov_b32_e32 v95, v2
	v_mov_b32_e32 v96, v2
	v_mov_b32_e32 v97, v2
	v_mov_b32_e32 v106, v2
	v_mov_b32_e32 v107, v2
	v_mov_b32_e32 v108, v2
	v_mov_b32_e32 v109, v2
	v_mov_b32_e32 v110, v2
	v_mov_b32_e32 v111, v2
	v_mov_b32_e32 v112, v2
	v_mov_b32_e32 v113, v2
	v_mov_b32_e32 v122, v2
	v_mov_b32_e32 v123, v2
	v_mov_b32_e32 v124, v2
	v_mov_b32_e32 v125, v2
	v_mov_b32_e32 v126, v2
	v_mov_b32_e32 v127, v2
	v_mov_b32_e32 v128, v2
	v_mov_b32_e32 v129, v2
	s_andn2_b64 vcc, exec, s[0:1]
	s_cbranch_vccnz .LBB0_1054
